# K1: GEMM K-loop LDS-DMA loads use SGPR-base (saddr) form, dropping per-piece v_lshl_add_u64
# speedup vs baseline: 1.0137x; 1.0137x over previous
; #define PG8_STAGE(bufoff, gbase, voff) do { _Pragma("unroll") for (int _i = 0; _i < 2; ++_i) \
;         __builtin_amdgcn_global_load_lds((const unsigned*)((const char*)(gbase) + (voff)[_i]), (PG8_LAS unsigned*)(lds + (bufoff) + ldsw + _i * 8192), 16, 0, 0); } while (0)
; #define PG8_WAIT_V(n) asm volatile("s_waitcnt vmcnt(" #n ")" ::: "memory")
; #define PG8_BAR __builtin_amdgcn_s_barrier()
; template <class Epi, class Sched, bool ALIGN_EPI = false, bool SP2 = false>
; __device__ __forceinline__ void gemm_phase(PG8_LAS unsigned char* lds, const Gemm g, const Sched& S, const Epi& E) {
;     ...
;     f32x4 acc[2][2][4][2];
; #pragma unroll
;     for (int a = 0; a < 2; ++a)
; #pragma unroll
;         for (int b = 0; b < 2; ++b)
; #pragma unroll
;             for (int m = 0; m < 4; ++m)
; #pragma unroll
;                 for (int n = 0; n < 2; ++n) acc[a][b][m][n] = (f32x4){0.f, 0.f, 0.f, 0.f};
;     ...
;         PG8_STAGE(PG8_SB(0, 0), cB, voffB); PG8_STAGE(PG8_SB(0, 1), cB + hstep, voffB); PG8_STAGE(PG8_SA(0, 0), cA, voffA); PG8_STAGE(PG8_SA(0, 1), cA + hstep, voffA);
;         if (wr == 1) PG8_BAR;
;         PG8_WAIT_V(2); PG8_BAR;
;         PG8_STAGE(PG8_SB(1, 0), cB + kstep, voffB); PG8_STAGE(PG8_SA(1, 0), cA + kstep, voffA); PG8_STAGE(PG8_SB(1, 1), cB + hstep + kstep, voffB);
;         PG8_WAIT_V(6); PG8_BAR;
.LBB0_896:
	s_add_u32 s6, s62, 0x17400000
	v_and_b32_e32 v1, 48, v0
	v_lshlrev_b32_e32 v2, 6, v0
	s_movk_i32 s5, 0x3c0
	v_lshlrev_b32_e32 v0, 2, v0
	s_addc_u32 s7, s63, 0
	s_lshl_b32 s42, s2, 6
	s_lshl_b32 s2, s2, 13
	v_and_or_b32 v1, v2, s5, v1
	v_and_b32_e32 v0, 32, v0
	v_bitop3_b32 v2, v1, s2, v0 bitop3:0xde
	s_lshl_b32 s2, s3, 5
	s_and_b32 s50, s2, 0x60
	s_lshl_b32 s2, s50, 7
	v_bitop3_b32 v206, s2, v1, v0 bitop3:0xf6
	s_add_u32 s2, s66, 0x8000
	v_mov_b32_e32 v163, v221
	s_addc_u32 s3, s67, 0
	s_add_i32 m0, s33, 0x18000
	v_lshl_add_u64 v[0:1], s[2:3], 0, v[162:163]
	v_mov_b32_e32 v167, v221
	s_waitcnt vmcnt(2)
	s_barrier
	global_load_lds_dwordx4 v[0:1], off
	s_add_i32 m0, s33, 0x1a000
	v_lshl_add_u64 v[0:1], s[2:3], 0, v[166:167]
	s_add_u32 s2, s18, 0x8000
	v_mov_b32_e32 v161, v221
	s_addc_u32 s3, s19, 0
	s_add_i32 s51, s33, 0x8000
	v_mov_b32_e32 v165, v221
	global_load_lds_dwordx4 v[0:1], off
	s_mov_b32 m0, s51
	s_add_i32 s52, s33, 0xa000
	global_load_lds_dwordx4 v160, s[2:3]
	v_lshl_add_u64 v[0:1], s[2:3], 0, v[164:165]
	s_add_u32 s2, s66, 0xc000
	s_mov_b32 m0, s52
	s_addc_u32 s3, s67, 0
	global_load_lds_dwordx4 v[0:1], off
	s_add_i32 m0, s33, 0x1c000
	s_nop 0
	global_load_lds_dwordx4 v162, s[2:3]
	s_add_i32 m0, s33, 0x1e000
	s_cmpk_lt_u32 s8, 0x100
	global_load_lds_dwordx4 v166, s[2:3]
	s_waitcnt vmcnt(6)
	s_cselect_b64 s[8:9], -1, 0
	s_add_u32 s53, s62, 0xa400a00
	v_mov_b32_e32 v0, 0
	s_addc_u32 s54, s63, 0
	s_ashr_i32 s55, s58, 31
	s_mov_b32 s56, 1
	v_add_u32_e32 v207, 0, v2
	v_mov_b32_e32 v1, v0
	v_mov_b32_e32 v2, v0
	v_mov_b32_e32 v3, v0
	v_mov_b32_e32 v4, v0
	v_mov_b32_e32 v5, v0
	v_mov_b32_e32 v6, v0
	v_mov_b32_e32 v7, v0
	v_mov_b32_e32 v8, v0
	v_mov_b32_e32 v9, v0
	v_mov_b32_e32 v10, v0
	v_mov_b32_e32 v11, v0
	v_mov_b32_e32 v12, v0
	v_mov_b32_e32 v13, v0
	v_mov_b32_e32 v14, v0
	v_mov_b32_e32 v15, v0
	v_mov_b32_e32 v16, v0
	v_mov_b32_e32 v17, v0
	v_mov_b32_e32 v18, v0
	v_mov_b32_e32 v19, v0
	v_mov_b32_e32 v20, v0
	v_mov_b32_e32 v21, v0
	v_mov_b32_e32 v22, v0
	v_mov_b32_e32 v23, v0
	v_mov_b32_e32 v24, v0
	v_mov_b32_e32 v25, v0
	v_mov_b32_e32 v26, v0
	v_mov_b32_e32 v27, v0
	v_mov_b32_e32 v28, v0
	v_mov_b32_e32 v29, v0
	v_mov_b32_e32 v30, v0
	v_mov_b32_e32 v31, v0
	v_mov_b32_e32 v32, v0
	v_mov_b32_e32 v33, v0
	v_mov_b32_e32 v34, v0
	v_mov_b32_e32 v35, v0
	v_mov_b32_e32 v36, v0
	v_mov_b32_e32 v37, v0
	v_mov_b32_e32 v38, v0
	v_mov_b32_e32 v39, v0
	v_mov_b32_e32 v40, v0
	v_mov_b32_e32 v41, v0
	v_mov_b32_e32 v42, v0
	v_mov_b32_e32 v43, v0
	v_mov_b32_e32 v44, v0
	v_mov_b32_e32 v45, v0
	v_mov_b32_e32 v46, v0
	v_mov_b32_e32 v47, v0
	v_mov_b32_e32 v48, v0
	v_mov_b32_e32 v49, v0
	v_mov_b32_e32 v50, v0
	v_mov_b32_e32 v51, v0
	v_mov_b32_e32 v52, v0
	v_mov_b32_e32 v53, v0
	v_mov_b32_e32 v54, v0
	v_mov_b32_e32 v55, v0
	v_mov_b32_e32 v56, v0
	v_mov_b32_e32 v57, v0
	v_mov_b32_e32 v58, v0
	v_mov_b32_e32 v59, v0
	v_mov_b32_e32 v60, v0
	v_mov_b32_e32 v61, v0
	v_mov_b32_e32 v62, v0
	v_mov_b32_e32 v63, v0
	v_mov_b32_e32 v64, v0
	v_mov_b32_e32 v65, v0
	v_mov_b32_e32 v66, v0
	v_mov_b32_e32 v67, v0
	v_mov_b32_e32 v68, v0
	v_mov_b32_e32 v69, v0
	v_mov_b32_e32 v70, v0
	v_mov_b32_e32 v71, v0
	v_mov_b32_e32 v72, v0
	v_mov_b32_e32 v73, v0
	v_mov_b32_e32 v74, v0
	v_mov_b32_e32 v75, v0
	v_mov_b32_e32 v76, v0
	v_mov_b32_e32 v77, v0
	v_mov_b32_e32 v78, v0
	v_mov_b32_e32 v79, v0
	v_mov_b32_e32 v80, v0
	v_mov_b32_e32 v81, v0
	v_mov_b32_e32 v82, v0
	v_mov_b32_e32 v83, v0
	v_mov_b32_e32 v84, v0
	v_mov_b32_e32 v85, v0
	v_mov_b32_e32 v86, v0
	v_mov_b32_e32 v87, v0
	v_mov_b32_e32 v88, v0
	v_mov_b32_e32 v89, v0
	v_mov_b32_e32 v90, v0
	v_mov_b32_e32 v91, v0
	v_mov_b32_e32 v92, v0
	v_mov_b32_e32 v93, v0
	v_mov_b32_e32 v94, v0
	v_mov_b32_e32 v95, v0
	v_mov_b32_e32 v96, v0
	v_mov_b32_e32 v97, v0
	v_mov_b32_e32 v98, v0
	v_mov_b32_e32 v99, v0
	v_mov_b32_e32 v100, v0
	v_mov_b32_e32 v101, v0
	v_mov_b32_e32 v102, v0
	v_mov_b32_e32 v103, v0
	v_mov_b32_e32 v104, v0
	v_mov_b32_e32 v105, v0
	v_mov_b32_e32 v106, v0
	v_mov_b32_e32 v107, v0
	v_mov_b32_e32 v108, v0
	v_mov_b32_e32 v109, v0
	v_mov_b32_e32 v110, v0
	v_mov_b32_e32 v111, v0
	v_mov_b32_e32 v112, v0
	v_mov_b32_e32 v113, v0
	v_mov_b32_e32 v114, v0
	v_mov_b32_e32 v115, v0
	v_mov_b32_e32 v116, v0
	v_mov_b32_e32 v117, v0
	v_mov_b32_e32 v118, v0
	v_mov_b32_e32 v119, v0
	v_mov_b32_e32 v120, v0
	v_mov_b32_e32 v121, v0
	v_mov_b32_e32 v122, v0
	v_mov_b32_e32 v123, v0
	v_mov_b32_e32 v124, v0
	v_mov_b32_e32 v125, v0
	v_mov_b32_e32 v126, v0
	v_mov_b32_e32 v127, v0
	s_barrier
	s_branch .LBB0_899

; #define PG8_STAGE(bufoff, gbase, voff) do { _Pragma("unroll") for (int _i = 0; _i < 2; ++_i) \
;         __builtin_amdgcn_global_load_lds((const unsigned*)((const char*)(gbase) + (voff)[_i]), (PG8_LAS unsigned*)(lds + (bufoff) + ldsw + _i * 8192), 16, 0, 0); } while (0)
; #define PG8_LDA(dst, b, h) do { _Pragma("unroll") for (int m = 0; m < 4; ++m) _Pragma("unroll") for (int k = 0; k < 2; ++k) dst[m][k] = *(const PG8_LAS bf16x8*)(lds + PG8_SA(b, h) + aoff + m * 2048 + k * 1024); } while (0)
; #define PG8_LDB(dst, b, h) do { _Pragma("unroll") for (int n = 0; n < 2; ++n) _Pragma("unroll") for (int k = 0; k < 2; ++k) dst[n][k] = *(const PG8_LAS bf16x8*)(lds + PG8_SB(b, h) + boff + n * 2048 + k * 1024); } while (0)
; #define PG8_MMA(ai, bj, At, Bt) do { __builtin_amdgcn_s_setprio(1); _Pragma("unroll") for (int m = 0; m < 4; ++m) _Pragma("unroll") for (int n = 0; n < 2; ++n) _Pragma("unroll") for (int k = 0; k < 2; ++k) \
;         acc[ai][bj][m][n] = __builtin_amdgcn_mfma_f32_16x16x32_bf16(Bt[n][k], At[m][k], acc[ai][bj][m][n], 0, 0, 0); __builtin_amdgcn_s_setprio(0); } while (0)
; #define PG8_BAR __builtin_amdgcn_s_barrier()
; template <class Epi, class Sched, bool ALIGN_EPI = false, bool SP2 = false>
; __device__ __forceinline__ void gemm_phase(PG8_LAS unsigned char* lds, const Gemm g, const Sched& S, const Epi& E) {
;     ...
;         const bool has_next = S.next(ui + 1, nxt);
;         const char* nA = has_next ? (const char*)g.A + (size_t)nxt.pm * tstep : cA; const char* nB = has_next ? (const char*)g.Bt + (size_t)nxt.pn * tstep : cB;
;         for (int t = 0; t < nt; t += 2) {
;             const bool last = (t == nt - 2);
;             const char* a1 = cA + (size_t)(t + 1) * kstep;
;             const char* a2 = last ? nA : cA + (size_t)(t + 2) * kstep; const char* b2 = last ? nB : cB + (size_t)(t + 2) * kstep;
;             const char* a3 = a2 + kstep; const char* b3 = b2 + kstep;
;             if (last && has_next) S.a_ready(nxt);
;             if constexpr (SP2) {
;             PG8_LDB(B0, 0, 0); PG8_LDB(B1, 0, 1); PG8_SCHED; PG8_LDA(At, 0, 0); PG8_STAGE(PG8_SA(1, 1), a1 + hstep, voffA);
;             PG8_WAIT_V(8); PG8_WAIT_L(0); PG8_BAR; PG8_MMA(0, 0, At, B0); PG8_MMA(0, 1, At, B1); PG8_BAR; PG8_SCHED;
;             PG8_LDA(At, 0, 1); PG8_STAGE(PG8_SB(0, 0), b2, voffB); PG8_STAGE(PG8_SB(0, 1), b2 + hstep, voffB); PG8_STAGE(PG8_SA(0, 0), a2, voffA);
.LBB0_905:
	s_ashr_i32 s13, s12, 31
	s_lshl_b64 s[14:15], s[12:13], 17
	s_add_u32 s14, s22, s14
	s_addc_u32 s15, s23, s15
	s_and_b64 s[16:17], s[2:3], exec
	s_cselect_b32 s71, s15, s19
	s_cselect_b32 s70, s14, s18
	s_ashr_i32 s11, s10, 31
	s_lshl_b64 s[16:17], s[10:11], 17
	s_add_u32 s16, s27, s16
	s_addc_u32 s17, s28, s17
	s_and_b64 s[64:65], s[2:3], exec
	s_cselect_b32 s69, s17, s67
	s_cselect_b32 s68, s16, s66
	s_add_u32 s74, s18, 0x10000
	s_addc_u32 s75, s19, 0
	s_add_u32 s76, s66, 0x10000
	s_addc_u32 s77, s67, 0
	s_add_u32 s72, s18, 0x18000
	s_addc_u32 s73, s19, 0
	s_add_i32 s59, 0, 0x10000
	s_add_i32 s13, 0, 0x14000
	v_add_u32_e32 v202, s59, v206
	v_add_u32_e32 v203, s13, v206
	ds_read_b128 v[128:131], v202
	ds_read_b128 v[132:135], v202 offset:1024
	ds_read_b128 v[136:139], v202 offset:2048
	ds_read_b128 v[140:143], v202 offset:3072
	ds_read_b128 v[144:147], v203
	ds_read_b128 v[148:151], v203 offset:1024
	ds_read_b128 v[152:155], v203 offset:2048
	ds_read_b128 v[156:159], v203 offset:3072
	s_add_u32 s80, s18, 0xc000
	s_addc_u32 s81, s19, 0
	s_add_i32 s64, s33, 0xc000
	s_mov_b32 m0, s64
	s_add_i32 s5, s33, 0xe000
	ds_read_b128 v[168:171], v207
	ds_read_b128 v[172:175], v207 offset:1024
	ds_read_b128 v[176:179], v207 offset:2048
	ds_read_b128 v[180:183], v207 offset:3072
	ds_read_b128 v[184:187], v207 offset:4096
	ds_read_b128 v[188:191], v207 offset:5120
	ds_read_b128 v[192:195], v207 offset:6144
	ds_read_b128 v[196:199], v207 offset:7168
	global_load_lds_dwordx4 v160, s[80:81]
	s_mov_b32 m0, s5
	s_nop 0
	global_load_lds_dwordx4 v164, s[80:81]
	s_waitcnt vmcnt(8)
	s_waitcnt lgkmcnt(0)
	s_barrier
	s_setprio 1
	s_waitcnt lgkmcnt(0)
	v_mfma_f32_16x16x32_bf16 v[124:127], v[128:131], v[168:171], v[124:127]
	v_mfma_f32_16x16x32_bf16 v[120:123], v[136:139], v[168:171], v[120:123]
	v_mfma_f32_16x16x32_bf16 v[116:119], v[128:131], v[176:179], v[116:119]
	v_mfma_f32_16x16x32_bf16 v[112:115], v[136:139], v[176:179], v[112:115]
	v_mfma_f32_16x16x32_bf16 v[108:111], v[128:131], v[184:187], v[108:111]
	v_mfma_f32_16x16x32_bf16 v[104:107], v[136:139], v[184:187], v[104:107]
	v_mfma_f32_16x16x32_bf16 v[100:103], v[128:131], v[192:195], v[100:103]
	v_mfma_f32_16x16x32_bf16 v[96:99], v[136:139], v[192:195], v[96:99]
	v_mfma_f32_16x16x32_bf16 v[124:127], v[132:135], v[172:175], v[124:127]
	v_mfma_f32_16x16x32_bf16 v[120:123], v[140:143], v[172:175], v[120:123]
	v_mfma_f32_16x16x32_bf16 v[116:119], v[132:135], v[180:183], v[116:119]
	v_mfma_f32_16x16x32_bf16 v[112:115], v[140:143], v[180:183], v[112:115]
	v_mfma_f32_16x16x32_bf16 v[108:111], v[132:135], v[188:191], v[108:111]
	v_mfma_f32_16x16x32_bf16 v[104:107], v[140:143], v[188:191], v[104:107]
	v_mfma_f32_16x16x32_bf16 v[100:103], v[132:135], v[196:199], v[100:103]
	v_mfma_f32_16x16x32_bf16 v[96:99], v[140:143], v[196:199], v[96:99]
	s_setprio 0
	s_setprio 1
	v_mfma_f32_16x16x32_bf16 v[92:95], v[144:147], v[168:171], v[92:95]
	v_mfma_f32_16x16x32_bf16 v[88:91], v[152:155], v[168:171], v[88:91]
	v_mfma_f32_16x16x32_bf16 v[84:87], v[144:147], v[176:179], v[84:87]
	v_mfma_f32_16x16x32_bf16 v[80:83], v[152:155], v[176:179], v[80:83]
	v_mfma_f32_16x16x32_bf16 v[76:79], v[144:147], v[184:187], v[76:79]
	v_mfma_f32_16x16x32_bf16 v[72:75], v[152:155], v[184:187], v[72:75]
	v_mfma_f32_16x16x32_bf16 v[68:71], v[144:147], v[192:195], v[68:71]
	v_mfma_f32_16x16x32_bf16 v[64:67], v[152:155], v[192:195], v[64:67]
	v_mfma_f32_16x16x32_bf16 v[92:95], v[148:151], v[172:175], v[92:95]
	v_mfma_f32_16x16x32_bf16 v[88:91], v[156:159], v[172:175], v[88:91]
	v_mfma_f32_16x16x32_bf16 v[84:87], v[148:151], v[180:183], v[84:87]
	v_mfma_f32_16x16x32_bf16 v[80:83], v[156:159], v[180:183], v[80:83]
	v_mfma_f32_16x16x32_bf16 v[76:79], v[148:151], v[188:191], v[76:79]
	v_mfma_f32_16x16x32_bf16 v[72:75], v[156:159], v[188:191], v[72:75]
	v_mfma_f32_16x16x32_bf16 v[68:71], v[148:151], v[196:199], v[68:71]
	v_mfma_f32_16x16x32_bf16 v[64:67], v[156:159], v[196:199], v[64:67]
	s_setprio 0
	s_barrier
	s_add_i32 s59, s59, s30
	s_mov_b32 m0, s59
	s_add_i32 s11, s59, 0x2000
	ds_read_b128 v[168:171], v207 offset:16384
	ds_read_b128 v[172:175], v207 offset:17408
	ds_read_b128 v[176:179], v207 offset:18432
	ds_read_b128 v[180:183], v207 offset:19456
	ds_read_b128 v[184:187], v207 offset:20480
	ds_read_b128 v[188:191], v207 offset:21504
	ds_read_b128 v[192:195], v207 offset:22528
	ds_read_b128 v[196:199], v207 offset:23552
	global_load_lds_dwordx4 v162, s[76:77]
	v_lshl_add_u64 v[200:201], s[76:77], 0, v[166:167]
	s_add_u32 s76, s66, 0x14000
	s_mov_b32 m0, s11
	s_addc_u32 s77, s67, 0
	s_add_i32 s13, s13, s30
	global_load_lds_dwordx4 v[200:201], off
	s_mov_b32 m0, s13
	s_add_i32 s21, s13, 0x2000
	global_load_lds_dwordx4 v162, s[76:77]
	s_mov_b32 m0, s21
	s_nop 0
	global_load_lds_dwordx4 v166, s[76:77]
	s_mov_b32 m0, s33
	s_nop 0
	global_load_lds_dwordx4 v160, s[74:75]
	s_mov_b32 m0, s37
	s_nop 0
	global_load_lds_dwordx4 v164, s[74:75]
	s_waitcnt vmcnt(8)
	s_waitcnt lgkmcnt(0)
	s_barrier
; #define PG8_STAGE(bufoff, gbase, voff) do { _Pragma("unroll") for (int _i = 0; _i < 2; ++_i) \
;         __builtin_amdgcn_global_load_lds((const unsigned*)((const char*)(gbase) + (voff)[_i]), (PG8_LAS unsigned*)(lds + (bufoff) + ldsw + _i * 8192), 16, 0, 0); } while (0)
; #define PG8_LDA(dst, b, h) do { _Pragma("unroll") for (int m = 0; m < 4; ++m) _Pragma("unroll") for (int k = 0; k < 2; ++k) dst[m][k] = *(const PG8_LAS bf16x8*)(lds + PG8_SA(b, h) + aoff + m * 2048 + k * 1024); } while (0)
; #define PG8_LDB(dst, b, h) do { _Pragma("unroll") for (int n = 0; n < 2; ++n) _Pragma("unroll") for (int k = 0; k < 2; ++k) dst[n][k] = *(const PG8_LAS bf16x8*)(lds + PG8_SB(b, h) + boff + n * 2048 + k * 1024); } while (0)
; #define PG8_MMA(ai, bj, At, Bt) do { __builtin_amdgcn_s_setprio(1); _Pragma("unroll") for (int m = 0; m < 4; ++m) _Pragma("unroll") for (int n = 0; n < 2; ++n) _Pragma("unroll") for (int k = 0; k < 2; ++k) \
;         acc[ai][bj][m][n] = __builtin_amdgcn_mfma_f32_16x16x32_bf16(Bt[n][k], At[m][k], acc[ai][bj][m][n], 0, 0, 0); __builtin_amdgcn_s_setprio(0); } while (0)
; #define PG8_WAIT_V(n) asm volatile("s_waitcnt vmcnt(" #n ")" ::: "memory")
; #define PG8_WAIT_L(n) asm volatile("s_waitcnt lgkmcnt(" #n ")" ::: "memory")
; #define PG8_BAR __builtin_amdgcn_s_barrier()
; #define PG8_SCHED __builtin_amdgcn_sched_barrier(0)
; template <class Epi, class Sched, bool ALIGN_EPI = false, bool SP2 = false>
; __device__ __forceinline__ void gemm_phase(PG8_LAS unsigned char* lds, const Gemm g, const Sched& S, const Epi& E) {
;     ...
;             PG8_WAIT_V(8); PG8_WAIT_L(0); PG8_BAR; PG8_MMA(1, 0, At, B0); PG8_MMA(1, 1, At, B1); PG8_BAR; PG8_SCHED;
;             PG8_LDB(B0, 1, 0); PG8_LDB(B1, 1, 1); PG8_SCHED; PG8_LDA(At, 1, 0); PG8_STAGE(PG8_SA(0, 1), a2 + hstep, voffA);
;             PG8_WAIT_V(8); PG8_WAIT_L(0); PG8_BAR; PG8_MMA(0, 0, At, B0); PG8_MMA(0, 1, At, B1); PG8_BAR; PG8_SCHED;
	s_setprio 1
	s_waitcnt lgkmcnt(0)
	v_mfma_f32_16x16x32_bf16 v[60:63], v[128:131], v[168:171], v[60:63]
	v_mfma_f32_16x16x32_bf16 v[56:59], v[136:139], v[168:171], v[56:59]
	v_mfma_f32_16x16x32_bf16 v[52:55], v[128:131], v[176:179], v[52:55]
	v_mfma_f32_16x16x32_bf16 v[48:51], v[136:139], v[176:179], v[48:51]
	v_mfma_f32_16x16x32_bf16 v[44:47], v[128:131], v[184:187], v[44:47]
	v_mfma_f32_16x16x32_bf16 v[40:43], v[136:139], v[184:187], v[40:43]
	v_mfma_f32_16x16x32_bf16 v[36:39], v[128:131], v[192:195], v[36:39]
	v_mfma_f32_16x16x32_bf16 v[32:35], v[136:139], v[192:195], v[32:35]
	v_mfma_f32_16x16x32_bf16 v[60:63], v[132:135], v[172:175], v[60:63]
	v_mfma_f32_16x16x32_bf16 v[56:59], v[140:143], v[172:175], v[56:59]
	v_mfma_f32_16x16x32_bf16 v[52:55], v[132:135], v[180:183], v[52:55]
	v_mfma_f32_16x16x32_bf16 v[48:51], v[140:143], v[180:183], v[48:51]
	v_mfma_f32_16x16x32_bf16 v[44:47], v[132:135], v[188:191], v[44:47]
	v_mfma_f32_16x16x32_bf16 v[40:43], v[140:143], v[188:191], v[40:43]
	v_mfma_f32_16x16x32_bf16 v[36:39], v[132:135], v[196:199], v[36:39]
	v_mfma_f32_16x16x32_bf16 v[32:35], v[140:143], v[196:199], v[32:35]
	s_setprio 0
	s_setprio 1
	v_mfma_f32_16x16x32_bf16 v[28:31], v[144:147], v[168:171], v[28:31]
	v_mfma_f32_16x16x32_bf16 v[24:27], v[152:155], v[168:171], v[24:27]
	v_mfma_f32_16x16x32_bf16 v[20:23], v[144:147], v[176:179], v[20:23]
	v_mfma_f32_16x16x32_bf16 v[16:19], v[152:155], v[176:179], v[16:19]
	v_mfma_f32_16x16x32_bf16 v[12:15], v[144:147], v[184:187], v[12:15]
	v_mfma_f32_16x16x32_bf16 v[8:11], v[152:155], v[184:187], v[8:11]
	v_mfma_f32_16x16x32_bf16 v[4:7], v[144:147], v[192:195], v[4:7]
	v_mfma_f32_16x16x32_bf16 v[0:3], v[152:155], v[192:195], v[0:3]
	v_mfma_f32_16x16x32_bf16 v[28:31], v[148:151], v[172:175], v[28:31]
	v_mfma_f32_16x16x32_bf16 v[24:27], v[156:159], v[172:175], v[24:27]
	v_mfma_f32_16x16x32_bf16 v[20:23], v[148:151], v[180:183], v[20:23]
	v_mfma_f32_16x16x32_bf16 v[16:19], v[156:159], v[180:183], v[16:19]
	v_mfma_f32_16x16x32_bf16 v[12:15], v[148:151], v[188:191], v[12:15]
	v_mfma_f32_16x16x32_bf16 v[8:11], v[156:159], v[188:191], v[8:11]
	v_mfma_f32_16x16x32_bf16 v[4:7], v[148:151], v[196:199], v[4:7]
	v_mfma_f32_16x16x32_bf16 v[0:3], v[156:159], v[196:199], v[0:3]
	s_setprio 0
	s_barrier
	s_add_i32 s65, 0, 0x18000
	s_add_i32 s57, 0, 0x1c000
	v_add_u32_e32 v204, s65, v206
	v_add_u32_e32 v205, s57, v206
	ds_read_b128 v[128:131], v204
	ds_read_b128 v[132:135], v204 offset:1024
	ds_read_b128 v[136:139], v204 offset:2048
	ds_read_b128 v[140:143], v204 offset:3072
	ds_read_b128 v[144:147], v205
	ds_read_b128 v[148:151], v205 offset:1024
	ds_read_b128 v[152:155], v205 offset:2048
	ds_read_b128 v[156:159], v205 offset:3072
	s_add_u32 s74, s18, 0x14000
	s_addc_u32 s75, s19, 0
	s_mov_b32 m0, s39
	ds_read_b128 v[168:171], v207 offset:32768
	ds_read_b128 v[172:175], v207 offset:33792
	ds_read_b128 v[176:179], v207 offset:34816
	ds_read_b128 v[180:183], v207 offset:35840
	ds_read_b128 v[184:187], v207 offset:36864
	ds_read_b128 v[188:191], v207 offset:37888
	ds_read_b128 v[192:195], v207 offset:38912
	ds_read_b128 v[196:199], v207 offset:39936
	global_load_lds_dwordx4 v160, s[74:75]
	s_mov_b32 m0, s41
	s_nop 0
	global_load_lds_dwordx4 v164, s[74:75]
	s_waitcnt vmcnt(8)
	s_waitcnt lgkmcnt(0)
	s_barrier
	s_setprio 1
	s_waitcnt lgkmcnt(0)
	v_mfma_f32_16x16x32_bf16 v[124:127], v[128:131], v[168:171], v[124:127]
	v_mfma_f32_16x16x32_bf16 v[120:123], v[136:139], v[168:171], v[120:123]
	v_mfma_f32_16x16x32_bf16 v[116:119], v[128:131], v[176:179], v[116:119]
	v_mfma_f32_16x16x32_bf16 v[112:115], v[136:139], v[176:179], v[112:115]
	v_mfma_f32_16x16x32_bf16 v[108:111], v[128:131], v[184:187], v[108:111]
	v_mfma_f32_16x16x32_bf16 v[104:107], v[136:139], v[184:187], v[104:107]
	v_mfma_f32_16x16x32_bf16 v[100:103], v[128:131], v[192:195], v[100:103]
	v_mfma_f32_16x16x32_bf16 v[96:99], v[136:139], v[192:195], v[96:99]
	v_mfma_f32_16x16x32_bf16 v[124:127], v[132:135], v[172:175], v[124:127]
	v_mfma_f32_16x16x32_bf16 v[120:123], v[140:143], v[172:175], v[120:123]
	v_mfma_f32_16x16x32_bf16 v[116:119], v[132:135], v[180:183], v[116:119]
	v_mfma_f32_16x16x32_bf16 v[112:115], v[140:143], v[180:183], v[112:115]
	v_mfma_f32_16x16x32_bf16 v[108:111], v[132:135], v[188:191], v[108:111]
	v_mfma_f32_16x16x32_bf16 v[104:107], v[140:143], v[188:191], v[104:107]
	v_mfma_f32_16x16x32_bf16 v[100:103], v[132:135], v[196:199], v[100:103]
	v_mfma_f32_16x16x32_bf16 v[96:99], v[140:143], v[196:199], v[96:99]
	s_setprio 0
	s_setprio 1
	v_mfma_f32_16x16x32_bf16 v[92:95], v[144:147], v[168:171], v[92:95]
	v_mfma_f32_16x16x32_bf16 v[88:91], v[152:155], v[168:171], v[88:91]
	v_mfma_f32_16x16x32_bf16 v[84:87], v[144:147], v[176:179], v[84:87]
	v_mfma_f32_16x16x32_bf16 v[80:83], v[152:155], v[176:179], v[80:83]
	v_mfma_f32_16x16x32_bf16 v[76:79], v[144:147], v[184:187], v[76:79]
	v_mfma_f32_16x16x32_bf16 v[72:75], v[152:155], v[184:187], v[72:75]
	v_mfma_f32_16x16x32_bf16 v[68:71], v[144:147], v[192:195], v[68:71]
	v_mfma_f32_16x16x32_bf16 v[64:67], v[152:155], v[192:195], v[64:67]
	v_mfma_f32_16x16x32_bf16 v[92:95], v[148:151], v[172:175], v[92:95]
	v_mfma_f32_16x16x32_bf16 v[88:91], v[156:159], v[172:175], v[88:91]
	v_mfma_f32_16x16x32_bf16 v[84:87], v[148:151], v[180:183], v[84:87]
	v_mfma_f32_16x16x32_bf16 v[80:83], v[156:159], v[180:183], v[80:83]
	v_mfma_f32_16x16x32_bf16 v[76:79], v[148:151], v[188:191], v[76:79]
	v_mfma_f32_16x16x32_bf16 v[72:75], v[156:159], v[188:191], v[72:75]
	v_mfma_f32_16x16x32_bf16 v[68:71], v[148:151], v[196:199], v[68:71]
	v_mfma_f32_16x16x32_bf16 v[64:67], v[156:159], v[196:199], v[64:67]
	s_setprio 0
	s_barrier
; #define PG8_STAGE(bufoff, gbase, voff) do { _Pragma("unroll") for (int _i = 0; _i < 2; ++_i) \
;         __builtin_amdgcn_global_load_lds((const unsigned*)((const char*)(gbase) + (voff)[_i]), (PG8_LAS unsigned*)(lds + (bufoff) + ldsw + _i * 8192), 16, 0, 0); } while (0)
; #define PG8_LDA(dst, b, h) do { _Pragma("unroll") for (int m = 0; m < 4; ++m) _Pragma("unroll") for (int k = 0; k < 2; ++k) dst[m][k] = *(const PG8_LAS bf16x8*)(lds + PG8_SA(b, h) + aoff + m * 2048 + k * 1024); } while (0)
; #define PG8_LDB(dst, b, h) do { _Pragma("unroll") for (int n = 0; n < 2; ++n) _Pragma("unroll") for (int k = 0; k < 2; ++k) dst[n][k] = *(const PG8_LAS bf16x8*)(lds + PG8_SB(b, h) + boff + n * 2048 + k * 1024); } while (0)
; #define PG8_MMA(ai, bj, At, Bt) do { __builtin_amdgcn_s_setprio(1); _Pragma("unroll") for (int m = 0; m < 4; ++m) _Pragma("unroll") for (int n = 0; n < 2; ++n) _Pragma("unroll") for (int k = 0; k < 2; ++k) \
;         acc[ai][bj][m][n] = __builtin_amdgcn_mfma_f32_16x16x32_bf16(Bt[n][k], At[m][k], acc[ai][bj][m][n], 0, 0, 0); __builtin_amdgcn_s_setprio(0); } while (0)
; #define PG8_WAIT_V(n) asm volatile("s_waitcnt vmcnt(" #n ")" ::: "memory")
; template <class Epi, class Sched, bool ALIGN_EPI = false, bool SP2 = false>
; __device__ __forceinline__ void gemm_phase(PG8_LAS unsigned char* lds, const Gemm g, const Sched& S, const Epi& E) {
;     ...
;             PG8_LDB(B0, 0, 0); PG8_LDB(B1, 0, 1); PG8_SCHED; PG8_LDA(At, 0, 0); PG8_STAGE(PG8_SA(1, 1), a1 + hstep, voffA);
;             PG8_WAIT_V(8); PG8_WAIT_L(0); PG8_BAR; PG8_MMA(0, 0, At, B0); PG8_MMA(0, 1, At, B1); PG8_BAR; PG8_SCHED;
;             PG8_LDA(At, 0, 1); PG8_STAGE(PG8_SB(0, 0), b2, voffB); PG8_STAGE(PG8_SB(0, 1), b2 + hstep, voffB); PG8_STAGE(PG8_SA(0, 0), a2, voffA);
;             PG8_WAIT_V(8); PG8_WAIT_L(0); PG8_BAR; PG8_MMA(1, 0, At, B0); PG8_MMA(1, 1, At, B1); PG8_BAR; PG8_SCHED;
;             PG8_LDB(B0, 1, 0); PG8_LDB(B1, 1, 1); PG8_SCHED; PG8_LDA(At, 1, 0); PG8_STAGE(PG8_SA(0, 1), a2 + hstep, voffA);
;             PG8_WAIT_V(8); PG8_WAIT_L(0); PG8_BAR; PG8_MMA(0, 0, At, B0); PG8_MMA(0, 1, At, B1); PG8_BAR; PG8_SCHED;
;             PG8_LDA(At, 1, 1); PG8_STAGE(PG8_SB(1, 0), b3, voffB); PG8_STAGE(PG8_SB(1, 1), b3 + hstep, voffB); PG8_STAGE(PG8_SA(1, 0), a3, voffA);
;             PG8_WAIT_V(8); PG8_WAIT_L(0); PG8_BAR; PG8_MMA(1, 0, At, B0); PG8_MMA(1, 1, At, B1); PG8_BAR; PG8_SCHED;
	s_add_u32 s74, s66, 0x18000
	s_addc_u32 s75, s67, 0
	s_add_i32 s65, s65, s30
	s_add_i32 s40, s65, 0x2000
	s_mov_b32 m0, s65
	s_add_u32 s66, s66, 0x1c000
	ds_read_b128 v[168:171], v207 offset:49152
	ds_read_b128 v[172:175], v207 offset:50176
	ds_read_b128 v[176:179], v207 offset:51200
	ds_read_b128 v[180:183], v207 offset:52224
	ds_read_b128 v[184:187], v207 offset:53248
	ds_read_b128 v[188:191], v207 offset:54272
	ds_read_b128 v[192:195], v207 offset:55296
	ds_read_b128 v[196:199], v207 offset:56320
	global_load_lds_dwordx4 v162, s[74:75]
	s_mov_b32 m0, s40
	s_addc_u32 s67, s67, 0
	s_add_i32 s57, s57, s30
	global_load_lds_dwordx4 v166, s[74:75]
	s_mov_b32 m0, s57
	s_add_i32 s61, s57, 0x2000
	global_load_lds_dwordx4 v162, s[66:67]
	s_mov_b32 m0, s61
	s_nop 0
	global_load_lds_dwordx4 v166, s[66:67]
	s_mov_b32 m0, s51
	s_nop 0
	global_load_lds_dwordx4 v160, s[72:73]
	s_mov_b32 m0, s52
	s_nop 0
	global_load_lds_dwordx4 v164, s[72:73]
	s_waitcnt vmcnt(8)
	s_waitcnt lgkmcnt(0)
	s_barrier
	s_setprio 1
	s_waitcnt lgkmcnt(0)
	v_mfma_f32_16x16x32_bf16 v[60:63], v[128:131], v[168:171], v[60:63]
	v_mfma_f32_16x16x32_bf16 v[56:59], v[136:139], v[168:171], v[56:59]
	v_mfma_f32_16x16x32_bf16 v[52:55], v[128:131], v[176:179], v[52:55]
	v_mfma_f32_16x16x32_bf16 v[48:51], v[136:139], v[176:179], v[48:51]
	v_mfma_f32_16x16x32_bf16 v[44:47], v[128:131], v[184:187], v[44:47]
	v_mfma_f32_16x16x32_bf16 v[40:43], v[136:139], v[184:187], v[40:43]
	v_mfma_f32_16x16x32_bf16 v[36:39], v[128:131], v[192:195], v[36:39]
	v_mfma_f32_16x16x32_bf16 v[32:35], v[136:139], v[192:195], v[32:35]
	v_mfma_f32_16x16x32_bf16 v[60:63], v[132:135], v[172:175], v[60:63]
	v_mfma_f32_16x16x32_bf16 v[56:59], v[140:143], v[172:175], v[56:59]
	v_mfma_f32_16x16x32_bf16 v[52:55], v[132:135], v[180:183], v[52:55]
	v_mfma_f32_16x16x32_bf16 v[48:51], v[140:143], v[180:183], v[48:51]
	v_mfma_f32_16x16x32_bf16 v[44:47], v[132:135], v[188:191], v[44:47]
	v_mfma_f32_16x16x32_bf16 v[40:43], v[140:143], v[188:191], v[40:43]
	v_mfma_f32_16x16x32_bf16 v[36:39], v[132:135], v[196:199], v[36:39]
	v_mfma_f32_16x16x32_bf16 v[32:35], v[140:143], v[196:199], v[32:35]
	s_setprio 0
	s_setprio 1
	v_mfma_f32_16x16x32_bf16 v[28:31], v[144:147], v[168:171], v[28:31]
	v_mfma_f32_16x16x32_bf16 v[24:27], v[152:155], v[168:171], v[24:27]
	v_mfma_f32_16x16x32_bf16 v[20:23], v[144:147], v[176:179], v[20:23]
	v_mfma_f32_16x16x32_bf16 v[16:19], v[152:155], v[176:179], v[16:19]
	v_mfma_f32_16x16x32_bf16 v[12:15], v[144:147], v[184:187], v[12:15]
	v_mfma_f32_16x16x32_bf16 v[8:11], v[152:155], v[184:187], v[8:11]
	v_mfma_f32_16x16x32_bf16 v[4:7], v[144:147], v[192:195], v[4:7]
	v_mfma_f32_16x16x32_bf16 v[0:3], v[152:155], v[192:195], v[0:3]
	v_mfma_f32_16x16x32_bf16 v[28:31], v[148:151], v[172:175], v[28:31]
	v_mfma_f32_16x16x32_bf16 v[24:27], v[156:159], v[172:175], v[24:27]
	v_mfma_f32_16x16x32_bf16 v[20:23], v[148:151], v[180:183], v[20:23]
	v_mfma_f32_16x16x32_bf16 v[16:19], v[156:159], v[180:183], v[16:19]
	v_mfma_f32_16x16x32_bf16 v[12:15], v[148:151], v[188:191], v[12:15]
	v_mfma_f32_16x16x32_bf16 v[8:11], v[156:159], v[188:191], v[8:11]
	v_mfma_f32_16x16x32_bf16 v[4:7], v[148:151], v[196:199], v[4:7]
	v_mfma_f32_16x16x32_bf16 v[0:3], v[156:159], v[196:199], v[0:3]
	s_setprio 0
	s_barrier
	ds_read_b128 v[128:131], v202
	ds_read_b128 v[132:135], v202 offset:1024
	ds_read_b128 v[136:139], v202 offset:2048
	ds_read_b128 v[140:143], v202 offset:3072
	ds_read_b128 v[144:147], v203
	ds_read_b128 v[148:151], v203 offset:1024
	ds_read_b128 v[152:155], v203 offset:2048
	ds_read_b128 v[156:159], v203 offset:3072
	s_add_u32 s66, s70, 0x8000
	s_addc_u32 s67, s71, 0
	s_add_u32 s18, s18, 0x1c000
	s_addc_u32 s19, s19, 0
	s_mov_b32 m0, s64
	ds_read_b128 v[168:171], v207
	ds_read_b128 v[172:175], v207 offset:1024
	ds_read_b128 v[176:179], v207 offset:2048
	ds_read_b128 v[180:183], v207 offset:3072
	ds_read_b128 v[184:187], v207 offset:4096
	ds_read_b128 v[188:191], v207 offset:5120
	ds_read_b128 v[192:195], v207 offset:6144
	ds_read_b128 v[196:199], v207 offset:7168
	global_load_lds_dwordx4 v160, s[18:19]
	s_mov_b32 m0, s5
	s_nop 0
	global_load_lds_dwordx4 v164, s[18:19]
	s_waitcnt vmcnt(8)
	s_waitcnt lgkmcnt(0)
	s_barrier
	s_setprio 1
	s_waitcnt lgkmcnt(0)
	v_mfma_f32_16x16x32_bf16 v[124:127], v[128:131], v[168:171], v[124:127]
	v_mfma_f32_16x16x32_bf16 v[120:123], v[136:139], v[168:171], v[120:123]
	v_mfma_f32_16x16x32_bf16 v[116:119], v[128:131], v[176:179], v[116:119]
	v_mfma_f32_16x16x32_bf16 v[112:115], v[136:139], v[176:179], v[112:115]
	v_mfma_f32_16x16x32_bf16 v[108:111], v[128:131], v[184:187], v[108:111]
	v_mfma_f32_16x16x32_bf16 v[104:107], v[136:139], v[184:187], v[104:107]
	v_mfma_f32_16x16x32_bf16 v[100:103], v[128:131], v[192:195], v[100:103]
	v_mfma_f32_16x16x32_bf16 v[96:99], v[136:139], v[192:195], v[96:99]
	v_mfma_f32_16x16x32_bf16 v[124:127], v[132:135], v[172:175], v[124:127]
	v_mfma_f32_16x16x32_bf16 v[120:123], v[140:143], v[172:175], v[120:123]
	v_mfma_f32_16x16x32_bf16 v[116:119], v[132:135], v[180:183], v[116:119]
	v_mfma_f32_16x16x32_bf16 v[112:115], v[140:143], v[180:183], v[112:115]
	v_mfma_f32_16x16x32_bf16 v[108:111], v[132:135], v[188:191], v[108:111]
	v_mfma_f32_16x16x32_bf16 v[104:107], v[140:143], v[188:191], v[104:107]
	v_mfma_f32_16x16x32_bf16 v[100:103], v[132:135], v[196:199], v[100:103]
	v_mfma_f32_16x16x32_bf16 v[96:99], v[140:143], v[196:199], v[96:99]
	s_setprio 0
	s_setprio 1
	v_mfma_f32_16x16x32_bf16 v[92:95], v[144:147], v[168:171], v[92:95]
	v_mfma_f32_16x16x32_bf16 v[88:91], v[152:155], v[168:171], v[88:91]
	v_mfma_f32_16x16x32_bf16 v[84:87], v[144:147], v[176:179], v[84:87]
	v_mfma_f32_16x16x32_bf16 v[80:83], v[152:155], v[176:179], v[80:83]
	v_mfma_f32_16x16x32_bf16 v[76:79], v[144:147], v[184:187], v[76:79]
	v_mfma_f32_16x16x32_bf16 v[72:75], v[152:155], v[184:187], v[72:75]
	v_mfma_f32_16x16x32_bf16 v[68:71], v[144:147], v[192:195], v[68:71]
	v_mfma_f32_16x16x32_bf16 v[64:67], v[152:155], v[192:195], v[64:67]
	v_mfma_f32_16x16x32_bf16 v[92:95], v[148:151], v[172:175], v[92:95]
	v_mfma_f32_16x16x32_bf16 v[88:91], v[156:159], v[172:175], v[88:91]
	v_mfma_f32_16x16x32_bf16 v[84:87], v[148:151], v[180:183], v[84:87]
	v_mfma_f32_16x16x32_bf16 v[80:83], v[156:159], v[180:183], v[80:83]
	v_mfma_f32_16x16x32_bf16 v[76:79], v[148:151], v[188:191], v[76:79]
	v_mfma_f32_16x16x32_bf16 v[72:75], v[156:159], v[188:191], v[72:75]
	v_mfma_f32_16x16x32_bf16 v[68:71], v[148:151], v[196:199], v[68:71]
	v_mfma_f32_16x16x32_bf16 v[64:67], v[156:159], v[196:199], v[64:67]
	s_setprio 0
	s_barrier
; #define PG8_STAGE(bufoff, gbase, voff) do { _Pragma("unroll") for (int _i = 0; _i < 2; ++_i) \
;         __builtin_amdgcn_global_load_lds((const unsigned*)((const char*)(gbase) + (voff)[_i]), (PG8_LAS unsigned*)(lds + (bufoff) + ldsw + _i * 8192), 16, 0, 0); } while (0)
; #define PG8_LDA(dst, b, h) do { _Pragma("unroll") for (int m = 0; m < 4; ++m) _Pragma("unroll") for (int k = 0; k < 2; ++k) dst[m][k] = *(const PG8_LAS bf16x8*)(lds + PG8_SA(b, h) + aoff + m * 2048 + k * 1024); } while (0)
; #define PG8_LDB(dst, b, h) do { _Pragma("unroll") for (int n = 0; n < 2; ++n) _Pragma("unroll") for (int k = 0; k < 2; ++k) dst[n][k] = *(const PG8_LAS bf16x8*)(lds + PG8_SB(b, h) + boff + n * 2048 + k * 1024); } while (0)
; #define PG8_MMA(ai, bj, At, Bt) do { __builtin_amdgcn_s_setprio(1); _Pragma("unroll") for (int m = 0; m < 4; ++m) _Pragma("unroll") for (int n = 0; n < 2; ++n) _Pragma("unroll") for (int k = 0; k < 2; ++k) \
;         acc[ai][bj][m][n] = __builtin_amdgcn_mfma_f32_16x16x32_bf16(Bt[n][k], At[m][k], acc[ai][bj][m][n], 0, 0, 0); __builtin_amdgcn_s_setprio(0); } while (0)
; #define PG8_WAIT_V(n) asm volatile("s_waitcnt vmcnt(" #n ")" ::: "memory")
; #define PG8_WAIT_L(n) asm volatile("s_waitcnt lgkmcnt(" #n ")" ::: "memory")
; #define PG8_BAR __builtin_amdgcn_s_barrier()
; #define PG8_SCHED __builtin_amdgcn_sched_barrier(0)
; template <class Epi, class Sched, bool ALIGN_EPI = false, bool SP2 = false>
; __device__ __forceinline__ void gemm_phase(PG8_LAS unsigned char* lds, const Gemm g, const Sched& S, const Epi& E) {
;     ...
;             PG8_LDA(At, 0, 1); PG8_STAGE(PG8_SB(0, 0), b2, voffB); PG8_STAGE(PG8_SB(0, 1), b2 + hstep, voffB); PG8_STAGE(PG8_SA(0, 0), a2, voffA);
;             PG8_WAIT_V(8); PG8_WAIT_L(0); PG8_BAR; PG8_MMA(1, 0, At, B0); PG8_MMA(1, 1, At, B1); PG8_BAR; PG8_SCHED;
;             PG8_LDB(B0, 1, 0); PG8_LDB(B1, 1, 1); PG8_SCHED; PG8_LDA(At, 1, 0); PG8_STAGE(PG8_SA(0, 1), a2 + hstep, voffA);
;             PG8_WAIT_V(8); PG8_WAIT_L(0); PG8_BAR; PG8_MMA(0, 0, At, B0); PG8_MMA(0, 1, At, B1); PG8_BAR; PG8_SCHED;
	s_mov_b32 m0, s59
	s_add_u32 s18, s68, 0x4000
	ds_read_b128 v[168:171], v207 offset:16384
	ds_read_b128 v[172:175], v207 offset:17408
	ds_read_b128 v[176:179], v207 offset:18432
	ds_read_b128 v[180:183], v207 offset:19456
	ds_read_b128 v[184:187], v207 offset:20480
	ds_read_b128 v[188:191], v207 offset:21504
	ds_read_b128 v[192:195], v207 offset:22528
	ds_read_b128 v[196:199], v207 offset:23552
	global_load_lds_dwordx4 v162, s[68:69]
	s_mov_b32 m0, s11
	s_addc_u32 s19, s69, 0
	global_load_lds_dwordx4 v166, s[68:69]
	s_mov_b32 m0, s13
	s_nop 0
	global_load_lds_dwordx4 v162, s[18:19]
	s_mov_b32 m0, s21
	s_nop 0
	global_load_lds_dwordx4 v166, s[18:19]
	s_mov_b32 m0, s33
	s_nop 0
	global_load_lds_dwordx4 v160, s[70:71]
	s_mov_b32 m0, s37
	s_nop 0
	global_load_lds_dwordx4 v164, s[70:71]
	s_waitcnt vmcnt(8)
	s_waitcnt lgkmcnt(0)
	s_barrier
	s_setprio 1
	s_waitcnt lgkmcnt(0)
	v_mfma_f32_16x16x32_bf16 v[60:63], v[128:131], v[168:171], v[60:63]
	v_mfma_f32_16x16x32_bf16 v[56:59], v[136:139], v[168:171], v[56:59]
	v_mfma_f32_16x16x32_bf16 v[52:55], v[128:131], v[176:179], v[52:55]
	v_mfma_f32_16x16x32_bf16 v[48:51], v[136:139], v[176:179], v[48:51]
	v_mfma_f32_16x16x32_bf16 v[44:47], v[128:131], v[184:187], v[44:47]
	v_mfma_f32_16x16x32_bf16 v[40:43], v[136:139], v[184:187], v[40:43]
	v_mfma_f32_16x16x32_bf16 v[36:39], v[128:131], v[192:195], v[36:39]
	v_mfma_f32_16x16x32_bf16 v[32:35], v[136:139], v[192:195], v[32:35]
	v_mfma_f32_16x16x32_bf16 v[60:63], v[132:135], v[172:175], v[60:63]
	v_mfma_f32_16x16x32_bf16 v[56:59], v[140:143], v[172:175], v[56:59]
	v_mfma_f32_16x16x32_bf16 v[52:55], v[132:135], v[180:183], v[52:55]
	v_mfma_f32_16x16x32_bf16 v[48:51], v[140:143], v[180:183], v[48:51]
	v_mfma_f32_16x16x32_bf16 v[44:47], v[132:135], v[188:191], v[44:47]
	v_mfma_f32_16x16x32_bf16 v[40:43], v[140:143], v[188:191], v[40:43]
	v_mfma_f32_16x16x32_bf16 v[36:39], v[132:135], v[196:199], v[36:39]
	v_mfma_f32_16x16x32_bf16 v[32:35], v[140:143], v[196:199], v[32:35]
	s_setprio 0
	s_setprio 1
	v_mfma_f32_16x16x32_bf16 v[28:31], v[144:147], v[168:171], v[28:31]
	v_mfma_f32_16x16x32_bf16 v[24:27], v[152:155], v[168:171], v[24:27]
	v_mfma_f32_16x16x32_bf16 v[20:23], v[144:147], v[176:179], v[20:23]
	v_mfma_f32_16x16x32_bf16 v[16:19], v[152:155], v[176:179], v[16:19]
	v_mfma_f32_16x16x32_bf16 v[12:15], v[144:147], v[184:187], v[12:15]
	v_mfma_f32_16x16x32_bf16 v[8:11], v[152:155], v[184:187], v[8:11]
	v_mfma_f32_16x16x32_bf16 v[4:7], v[144:147], v[192:195], v[4:7]
	v_mfma_f32_16x16x32_bf16 v[0:3], v[152:155], v[192:195], v[0:3]
	v_mfma_f32_16x16x32_bf16 v[28:31], v[148:151], v[172:175], v[28:31]
	v_mfma_f32_16x16x32_bf16 v[24:27], v[156:159], v[172:175], v[24:27]
	v_mfma_f32_16x16x32_bf16 v[20:23], v[148:151], v[180:183], v[20:23]
	v_mfma_f32_16x16x32_bf16 v[16:19], v[156:159], v[180:183], v[16:19]
	v_mfma_f32_16x16x32_bf16 v[12:15], v[148:151], v[188:191], v[12:15]
	v_mfma_f32_16x16x32_bf16 v[8:11], v[156:159], v[188:191], v[8:11]
	v_mfma_f32_16x16x32_bf16 v[4:7], v[148:151], v[196:199], v[4:7]
	v_mfma_f32_16x16x32_bf16 v[0:3], v[156:159], v[196:199], v[0:3]
	s_setprio 0
	s_barrier
	ds_read_b128 v[128:131], v204
	ds_read_b128 v[132:135], v204 offset:1024
	ds_read_b128 v[136:139], v204 offset:2048
	ds_read_b128 v[140:143], v204 offset:3072
	ds_read_b128 v[144:147], v205
	ds_read_b128 v[148:151], v205 offset:1024
	ds_read_b128 v[152:155], v205 offset:2048
	ds_read_b128 v[156:159], v205 offset:3072
	s_add_u32 s18, s70, 0x4000
	s_addc_u32 s19, s71, 0
	s_mov_b32 m0, s39
	ds_read_b128 v[168:171], v207 offset:32768
	ds_read_b128 v[172:175], v207 offset:33792
	ds_read_b128 v[176:179], v207 offset:34816
	ds_read_b128 v[180:183], v207 offset:35840
	ds_read_b128 v[184:187], v207 offset:36864
	ds_read_b128 v[188:191], v207 offset:37888
	ds_read_b128 v[192:195], v207 offset:38912
	ds_read_b128 v[196:199], v207 offset:39936
	global_load_lds_dwordx4 v160, s[18:19]
	s_mov_b32 m0, s41
	s_nop 0
	global_load_lds_dwordx4 v164, s[18:19]
	s_waitcnt vmcnt(8)
	s_waitcnt lgkmcnt(0)
	s_barrier
; #define PG8_STAGE(bufoff, gbase, voff) do { _Pragma("unroll") for (int _i = 0; _i < 2; ++_i) \
;         __builtin_amdgcn_global_load_lds((const unsigned*)((const char*)(gbase) + (voff)[_i]), (PG8_LAS unsigned*)(lds + (bufoff) + ldsw + _i * 8192), 16, 0, 0); } while (0)
; #define PG8_LDA(dst, b, h) do { _Pragma("unroll") for (int m = 0; m < 4; ++m) _Pragma("unroll") for (int k = 0; k < 2; ++k) dst[m][k] = *(const PG8_LAS bf16x8*)(lds + PG8_SA(b, h) + aoff + m * 2048 + k * 1024); } while (0)
; #define PG8_MMA(ai, bj, At, Bt) do { __builtin_amdgcn_s_setprio(1); _Pragma("unroll") for (int m = 0; m < 4; ++m) _Pragma("unroll") for (int n = 0; n < 2; ++n) _Pragma("unroll") for (int k = 0; k < 2; ++k) \
;         acc[ai][bj][m][n] = __builtin_amdgcn_mfma_f32_16x16x32_bf16(Bt[n][k], At[m][k], acc[ai][bj][m][n], 0, 0, 0); __builtin_amdgcn_s_setprio(0); } while (0)
; #define PG8_WAIT_V(n) asm volatile("s_waitcnt vmcnt(" #n ")" ::: "memory")
; #define PG8_WAIT_L(n) asm volatile("s_waitcnt lgkmcnt(" #n ")" ::: "memory")
; #define PG8_BAR __builtin_amdgcn_s_barrier()
; #define PG8_SCHED __builtin_amdgcn_sched_barrier(0)
; template <class Epi, class Sched, bool ALIGN_EPI = false, bool SP2 = false>
; __device__ __forceinline__ void gemm_phase(PG8_LAS unsigned char* lds, const Gemm g, const Sched& S, const Epi& E) {
;     ...
;             PG8_WAIT_V(8); PG8_WAIT_L(0); PG8_BAR; PG8_MMA(0, 0, At, B0); PG8_MMA(0, 1, At, B1); PG8_BAR; PG8_SCHED;
;             PG8_LDA(At, 1, 1); PG8_STAGE(PG8_SB(1, 0), b3, voffB); PG8_STAGE(PG8_SB(1, 1), b3 + hstep, voffB); PG8_STAGE(PG8_SA(1, 0), a3, voffA);
;             PG8_WAIT_V(8); PG8_WAIT_L(0); PG8_BAR; PG8_MMA(1, 0, At, B0); PG8_MMA(1, 1, At, B1); PG8_BAR; PG8_SCHED;
;     ...
;         if constexpr (ALIGN_EPI) { if (wr == 0) PG8_BAR; }
	s_setprio 1
	s_waitcnt lgkmcnt(0)
	v_mfma_f32_16x16x32_bf16 v[124:127], v[128:131], v[168:171], v[124:127]
	v_mfma_f32_16x16x32_bf16 v[120:123], v[136:139], v[168:171], v[120:123]
	v_mfma_f32_16x16x32_bf16 v[116:119], v[128:131], v[176:179], v[116:119]
	v_mfma_f32_16x16x32_bf16 v[112:115], v[136:139], v[176:179], v[112:115]
	v_mfma_f32_16x16x32_bf16 v[108:111], v[128:131], v[184:187], v[108:111]
	v_mfma_f32_16x16x32_bf16 v[104:107], v[136:139], v[184:187], v[104:107]
	v_mfma_f32_16x16x32_bf16 v[100:103], v[128:131], v[192:195], v[100:103]
	v_mfma_f32_16x16x32_bf16 v[96:99], v[136:139], v[192:195], v[96:99]
	v_mfma_f32_16x16x32_bf16 v[124:127], v[132:135], v[172:175], v[124:127]
	v_mfma_f32_16x16x32_bf16 v[120:123], v[140:143], v[172:175], v[120:123]
	v_mfma_f32_16x16x32_bf16 v[116:119], v[132:135], v[180:183], v[116:119]
	v_mfma_f32_16x16x32_bf16 v[112:115], v[140:143], v[180:183], v[112:115]
	v_mfma_f32_16x16x32_bf16 v[108:111], v[132:135], v[188:191], v[108:111]
	v_mfma_f32_16x16x32_bf16 v[104:107], v[140:143], v[188:191], v[104:107]
	v_mfma_f32_16x16x32_bf16 v[100:103], v[132:135], v[196:199], v[100:103]
	v_mfma_f32_16x16x32_bf16 v[96:99], v[140:143], v[196:199], v[96:99]
	s_setprio 0
	s_setprio 1
	v_mfma_f32_16x16x32_bf16 v[92:95], v[144:147], v[168:171], v[92:95]
	v_mfma_f32_16x16x32_bf16 v[88:91], v[152:155], v[168:171], v[88:91]
	v_mfma_f32_16x16x32_bf16 v[84:87], v[144:147], v[176:179], v[84:87]
	v_mfma_f32_16x16x32_bf16 v[80:83], v[152:155], v[176:179], v[80:83]
	v_mfma_f32_16x16x32_bf16 v[76:79], v[144:147], v[184:187], v[76:79]
	v_mfma_f32_16x16x32_bf16 v[72:75], v[152:155], v[184:187], v[72:75]
	v_mfma_f32_16x16x32_bf16 v[68:71], v[144:147], v[192:195], v[68:71]
	v_mfma_f32_16x16x32_bf16 v[64:67], v[152:155], v[192:195], v[64:67]
	v_mfma_f32_16x16x32_bf16 v[92:95], v[148:151], v[172:175], v[92:95]
	v_mfma_f32_16x16x32_bf16 v[88:91], v[156:159], v[172:175], v[88:91]
	v_mfma_f32_16x16x32_bf16 v[84:87], v[148:151], v[180:183], v[84:87]
	v_mfma_f32_16x16x32_bf16 v[80:83], v[156:159], v[180:183], v[80:83]
	v_mfma_f32_16x16x32_bf16 v[76:79], v[148:151], v[188:191], v[76:79]
	v_mfma_f32_16x16x32_bf16 v[72:75], v[156:159], v[188:191], v[72:75]
	v_mfma_f32_16x16x32_bf16 v[68:71], v[148:151], v[196:199], v[68:71]
	v_mfma_f32_16x16x32_bf16 v[64:67], v[156:159], v[196:199], v[64:67]
	s_setprio 0
	s_barrier
	s_add_u32 s18, s68, 0x8000
	s_addc_u32 s19, s69, 0
	s_mov_b32 m0, s65
	ds_read_b128 v[168:171], v207 offset:49152
	ds_read_b128 v[172:175], v207 offset:50176
	ds_read_b128 v[176:179], v207 offset:51200
	ds_read_b128 v[180:183], v207 offset:52224
	ds_read_b128 v[184:187], v207 offset:53248
	ds_read_b128 v[188:191], v207 offset:54272
	ds_read_b128 v[192:195], v207 offset:55296
	ds_read_b128 v[196:199], v207 offset:56320
	global_load_lds_dwordx4 v162, s[18:19]
	v_lshl_add_u64 v[200:201], s[18:19], 0, v[166:167]
	s_add_u32 s18, s68, 0xc000
	s_mov_b32 m0, s40
	s_addc_u32 s19, s69, 0
	global_load_lds_dwordx4 v[200:201], off
	s_mov_b32 m0, s57
	s_nop 0
	global_load_lds_dwordx4 v162, s[18:19]
	s_mov_b32 m0, s61
	s_nop 0
	global_load_lds_dwordx4 v166, s[18:19]
	s_mov_b32 m0, s51
	s_nop 0
	global_load_lds_dwordx4 v160, s[66:67]
	s_mov_b32 m0, s52
	s_nop 0
	global_load_lds_dwordx4 v164, s[66:67]
	s_waitcnt vmcnt(8)
	s_waitcnt lgkmcnt(0)
	s_barrier
	s_setprio 1
	s_waitcnt lgkmcnt(0)
	v_mfma_f32_16x16x32_bf16 v[60:63], v[128:131], v[168:171], v[60:63]
	v_mfma_f32_16x16x32_bf16 v[56:59], v[136:139], v[168:171], v[56:59]
	v_mfma_f32_16x16x32_bf16 v[52:55], v[128:131], v[176:179], v[52:55]
	v_mfma_f32_16x16x32_bf16 v[48:51], v[136:139], v[176:179], v[48:51]
	v_mfma_f32_16x16x32_bf16 v[44:47], v[128:131], v[184:187], v[44:47]
	v_mfma_f32_16x16x32_bf16 v[40:43], v[136:139], v[184:187], v[40:43]
	v_mfma_f32_16x16x32_bf16 v[36:39], v[128:131], v[192:195], v[36:39]
	v_mfma_f32_16x16x32_bf16 v[32:35], v[136:139], v[192:195], v[32:35]
	v_mfma_f32_16x16x32_bf16 v[60:63], v[132:135], v[172:175], v[60:63]
	v_mfma_f32_16x16x32_bf16 v[56:59], v[140:143], v[172:175], v[56:59]
	v_mfma_f32_16x16x32_bf16 v[52:55], v[132:135], v[180:183], v[52:55]
	v_mfma_f32_16x16x32_bf16 v[48:51], v[140:143], v[180:183], v[48:51]
	v_mfma_f32_16x16x32_bf16 v[44:47], v[132:135], v[188:191], v[44:47]
	v_mfma_f32_16x16x32_bf16 v[40:43], v[140:143], v[188:191], v[40:43]
	v_mfma_f32_16x16x32_bf16 v[36:39], v[132:135], v[196:199], v[36:39]
	v_mfma_f32_16x16x32_bf16 v[32:35], v[140:143], v[196:199], v[32:35]
	s_setprio 0
	s_setprio 1
	v_mfma_f32_16x16x32_bf16 v[28:31], v[144:147], v[168:171], v[28:31]
	v_mfma_f32_16x16x32_bf16 v[24:27], v[152:155], v[168:171], v[24:27]
	v_mfma_f32_16x16x32_bf16 v[20:23], v[144:147], v[176:179], v[20:23]
	v_mfma_f32_16x16x32_bf16 v[16:19], v[152:155], v[176:179], v[16:19]
	v_mfma_f32_16x16x32_bf16 v[12:15], v[144:147], v[184:187], v[12:15]
	v_mfma_f32_16x16x32_bf16 v[8:11], v[152:155], v[184:187], v[8:11]
	v_mfma_f32_16x16x32_bf16 v[4:7], v[144:147], v[192:195], v[4:7]
	v_mfma_f32_16x16x32_bf16 v[0:3], v[152:155], v[192:195], v[0:3]
	v_mfma_f32_16x16x32_bf16 v[28:31], v[148:151], v[172:175], v[28:31]
	v_mfma_f32_16x16x32_bf16 v[24:27], v[156:159], v[172:175], v[24:27]
	v_mfma_f32_16x16x32_bf16 v[20:23], v[148:151], v[180:183], v[20:23]
	v_mfma_f32_16x16x32_bf16 v[16:19], v[156:159], v[180:183], v[16:19]
	v_mfma_f32_16x16x32_bf16 v[12:15], v[148:151], v[188:191], v[12:15]
	v_mfma_f32_16x16x32_bf16 v[8:11], v[156:159], v[188:191], v[8:11]
	v_mfma_f32_16x16x32_bf16 v[4:7], v[148:151], v[196:199], v[4:7]
	v_mfma_f32_16x16x32_bf16 v[0:3], v[156:159], v[196:199], v[0:3]
	s_setprio 0
	s_barrier
	s_andn2_b64 vcc, exec, s[8:9]
	s_cbranch_vccnz .LBB0_907
	s_barrier

; #define PG8_STAGE(bufoff, gbase, voff) do { _Pragma("unroll") for (int _i = 0; _i < 2; ++_i) \
;         __builtin_amdgcn_global_load_lds((const unsigned*)((const char*)(gbase) + (voff)[_i]), (PG8_LAS unsigned*)(lds + (bufoff) + ldsw + _i * 8192), 16, 0, 0); } while (0)
; #define PG8_WAIT_V(n) asm volatile("s_waitcnt vmcnt(" #n ")" ::: "memory")
; #define PG8_BAR __builtin_amdgcn_s_barrier()
;     __device__ void init(int M, int N, int G_, int c_) { base.init(M, N, G_, c_); }
; #define P_IN(i) ((const float*)rd_ptr(i))
; template <class Epi, class Sched, bool ALIGN_EPI = false, bool SP2 = false>
; __device__ __forceinline__ void gemm_phase(PG8_LAS unsigned char* lds, const Gemm g, const Sched& S, const Epi& E) {
;     ...
;         PG8_STAGE(PG8_SB(1, 0), cB + kstep, voffB); PG8_STAGE(PG8_SA(1, 0), cA + kstep, voffA); PG8_STAGE(PG8_SB(1, 1), cB + hstep + kstep, voffB);
;         PG8_WAIT_V(6); PG8_BAR;
;     } else {
;         PG8_STAGE(PG8_SB(0, 0), cB, voffB); PG8_STAGE(PG8_SA(0, 0), cA, voffA); PG8_STAGE(PG8_SB(0, 1), cB + hstep, voffB); PG8_STAGE(PG8_SA(0, 1), cA + hstep, voffA);
;         if (wr == 1) PG8_BAR;
;         PG8_WAIT_V(4); PG8_BAR;
;         PG8_STAGE(PG8_SB(1, 0), cB + kstep, voffB); PG8_STAGE(PG8_SA(1, 0), cA + kstep, voffA); PG8_STAGE(PG8_SB(1, 1), cB + hstep + kstep, voffB);
;         PG8_WAIT_V(6); PG8_BAR;
;     }
; __global__ void __launch_bounds__(NTHR, 2) trunk_fwd(Args args) {
;     ...
;             pg8::Gemm g{(const u16*)(ws + WS_XB) + hrow * DM, (const u16*)(wl + WO_IN), MH, 24 * 256, DM}; pg8::StaticOrder S; S.init(MH, 24 * 256, G, bx);
;             pg8::EpiWin E{(u16*)(ws + WS_ZA), (u16*)(ws + WS_QC), (u16*)(ws + WS_KC), (u16*)(ws + WS_VC), (float*)(ws + WS_MIF), (const float*)(ws + WS_SSP) + hrow * 16, (const float*)(ws + WS_COS) + hrow * 32, (const float*)(ws + WS_SIN) + hrow * 32, P_IN(11) + l * 8};
.LBB0_1124:
	s_add_u32 s12, s62, 0xa400000
	s_addc_u32 s13, s63, 0
	s_add_u32 s28, s62, 0x17400000
	s_addc_u32 s52, s63, 0
	s_add_u32 s54, s62, 0x18400000
	s_addc_u32 s41, s63, 0
	s_add_u32 s14, s62, 0x1dc00000
	v_readlane_b32 s18, v255, 13
	s_addc_u32 s15, s63, 0
	s_lshl_b32 s1, s18, 6
	s_add_u32 s1, s62, s1
	s_addc_u32 s5, s63, 0
	s_add_u32 s16, s1, 0x1e500000
	s_addc_u32 s17, s5, 0
	s_lshl_b32 s1, s18, 7
	s_add_u32 s1, s62, s1
	s_addc_u32 s5, s63, 0
	v_readlane_b32 s19, v255, 14
	s_add_u32 s18, s1, 0x1dd00000
	s_addc_u32 s19, s5, 0
	s_add_u32 s20, s1, 0x1e100000
	s_addc_u32 s21, s5, 0
	s_lshl_b32 s30, s78, 3
	s_lshl_b64 s[50:51], s[30:31], 2
	s_add_u32 s66, s22, s50
	s_addc_u32 s67, s3, s51
	s_and_b32 s51, s23, 3
	s_lshl_b32 s1, s0, 6
	s_lshl_b32 s3, s0, 13
	s_lshl_b32 s68, s51, 5
	s_lshl_b32 s5, s51, 12
	s_add_u32 s0, s10, 0x8000
	v_mov_b32_e32 v171, v221
	v_writelane_b32 v255, s1, 18
	s_addc_u32 s1, s11, 0
	s_add_i32 m0, s33, 0x18000
	v_lshl_add_u64 v[8:9], s[0:1], 0, v[170:171]
	v_mov_b32_e32 v175, v221
	s_waitcnt vmcnt(2)
	s_barrier
	global_load_lds_dwordx4 v[8:9], off
	s_add_i32 m0, s33, 0x1a000
	v_lshl_add_u64 v[8:9], s[0:1], 0, v[174:175]
	s_add_u32 s0, s6, 0x8000
	v_mov_b32_e32 v169, v221
	s_addc_u32 s1, s7, 0
	s_add_i32 s53, s33, 0x8000
	v_mov_b32_e32 v173, v221
	global_load_lds_dwordx4 v[8:9], off
	s_mov_b32 m0, s53
	s_add_i32 s27, s33, 0xa000
	global_load_lds_dwordx4 v168, s[0:1]
	v_lshl_add_u64 v[8:9], s[0:1], 0, v[172:173]
	s_add_u32 s0, s10, 0xc000
	s_mov_b32 m0, s27
	s_addc_u32 s1, s11, 0
	global_load_lds_dwordx4 v[8:9], off
	s_add_i32 m0, s33, 0x1c000
	s_nop 0
	global_load_lds_dwordx4 v170, s[0:1]
	s_add_i32 m0, s33, 0x1e000
	v_and_b32_e32 v7, 48, v0
	global_load_lds_dwordx4 v174, s[0:1]
	v_lshlrev_b32_e32 v8, 6, v0
	s_movk_i32 s0, 0x3c0
	v_lshlrev_b32_e32 v0, 2, v0
	s_cmpk_lt_u32 s2, 0x100
	v_and_or_b32 v7, v8, s0, v7
	v_and_b32_e32 v0, 32, v0
	s_cselect_b64 s[70:71], -1, 0
	s_lshl_b32 s0, s23, 11
	v_bitop3_b32 v8, v7, s3, v0 bitop3:0xde
	v_bitop3_b32 v192, v7, s5, v0 bitop3:0xde
	s_and_b32 s0, s0, 0x1000
	v_lshlrev_b32_e32 v0, 10, v1
	s_or_b32 s0, s0, 0xfffdc000
	v_and_b32_e32 v0, 0xfffff800, v0
	s_cmp_eq_u32 s51, 0
	v_lshl_add_u32 v0, v2, 7, v0
	v_and_b32_e32 v1, 1, v1
	s_cselect_b64 s[72:73], -1, 0
	s_lshl_b32 s2, s23, 6
	v_lshl_or_b32 v0, v1, 6, v0
	s_ashr_i32 s39, s60, 31
	s_ashr_i32 s50, s58, 31
	s_and_b32 s2, s2, 64
	v_lshl_add_u32 v176, v3, 1, v0
	v_lshlrev_b32_e32 v0, 10, v4
	s_add_u32 s2, s62, s2
	v_and_b32_e32 v0, 0xfffff800, v0
	s_waitcnt vmcnt(6)
	s_addc_u32 s3, s63, 0
	v_lshl_add_u32 v0, v5, 7, v0
	v_and_b32_e32 v1, 1, v4
	s_add_u32 s74, s2, 0x19400000
	v_lshl_or_b32 v0, v1, 6, v0
	s_mov_b32 s69, s31
	s_mov_b32 s1, 0
	s_addc_u32 s75, s3, 0
	v_mov_b32_e32 v177, v221
	v_lshl_add_u32 v178, v6, 1, v0
	v_mov_b32_e32 v179, v221
	v_add_u32_e32 v193, 0, v8
	s_barrier
	s_branch .LBB0_1127

; #define PG8_STAGE(bufoff, gbase, voff) do { _Pragma("unroll") for (int _i = 0; _i < 2; ++_i) \
;         __builtin_amdgcn_global_load_lds((const unsigned*)((const char*)(gbase) + (voff)[_i]), (PG8_LAS unsigned*)(lds + (bufoff) + ldsw + _i * 8192), 16, 0, 0); } while (0)
; #define PG8_LDA(dst, b, h) do { _Pragma("unroll") for (int m = 0; m < 4; ++m) _Pragma("unroll") for (int k = 0; k < 2; ++k) dst[m][k] = *(const PG8_LAS bf16x8*)(lds + PG8_SA(b, h) + aoff + m * 2048 + k * 1024); } while (0)
; #define PG8_LDB(dst, b, h) do { _Pragma("unroll") for (int n = 0; n < 2; ++n) _Pragma("unroll") for (int k = 0; k < 2; ++k) dst[n][k] = *(const PG8_LAS bf16x8*)(lds + PG8_SB(b, h) + boff + n * 2048 + k * 1024); } while (0)
; #define PG8_MMA(ai, bj, At, Bt) do { __builtin_amdgcn_s_setprio(1); _Pragma("unroll") for (int m = 0; m < 4; ++m) _Pragma("unroll") for (int n = 0; n < 2; ++n) _Pragma("unroll") for (int k = 0; k < 2; ++k) \
;         acc[ai][bj][m][n] = __builtin_amdgcn_mfma_f32_16x16x32_bf16(Bt[n][k], At[m][k], acc[ai][bj][m][n], 0, 0, 0); __builtin_amdgcn_s_setprio(0); } while (0)
; #define PG8_WAIT_V(n) asm volatile("s_waitcnt vmcnt(" #n ")" ::: "memory")
; #define PG8_BAR __builtin_amdgcn_s_barrier()
; template <class Epi, class Sched, bool ALIGN_EPI = false, bool SP2 = false>
; __device__ __forceinline__ void gemm_phase(PG8_LAS unsigned char* lds, const Gemm g, const Sched& S, const Epi& E) {
;     ...
;         for (int t = 0; t < nt; t += 2) {
;             const bool last = (t == nt - 2);
;             const char* a1 = cA + (size_t)(t + 1) * kstep;
;             const char* a2 = last ? nA : cA + (size_t)(t + 2) * kstep; const char* b2 = last ? nB : cB + (size_t)(t + 2) * kstep;
;             const char* a3 = a2 + kstep; const char* b3 = b2 + kstep;
;             if (last && has_next) S.a_ready(nxt);
;             if constexpr (SP2) {
;             PG8_LDB(B0, 0, 0); PG8_LDB(B1, 0, 1); PG8_SCHED; PG8_LDA(At, 0, 0); PG8_STAGE(PG8_SA(1, 1), a1 + hstep, voffA);
;             PG8_WAIT_V(8); PG8_WAIT_L(0); PG8_BAR; PG8_MMA(0, 0, At, B0); PG8_MMA(0, 1, At, B1); PG8_BAR; PG8_SCHED;
;             PG8_LDA(At, 0, 1); PG8_STAGE(PG8_SB(0, 0), b2, voffB); PG8_STAGE(PG8_SB(0, 1), b2 + hstep, voffB); PG8_STAGE(PG8_SA(0, 0), a2, voffA);
;             PG8_WAIT_V(8); PG8_WAIT_L(0); PG8_BAR; PG8_MMA(1, 0, At, B0); PG8_MMA(1, 1, At, B1); PG8_BAR; PG8_SCHED;
.LBB0_1130:
	s_add_u32 s10, s6, 0x4000
	s_addc_u32 s11, s7, 0
	s_cmp_eq_u32 s40, 12
	s_cselect_b32 s86, s9, s10
	s_cselect_b32 s87, s5, s11
	s_cselect_b32 s84, s23, s30
	s_cselect_b32 s85, s22, s37
	s_add_u32 s10, s86, 0x8000
	s_addc_u32 s11, s87, 0
	s_add_i32 s77, 0, 0x10000
	s_add_i32 s79, 0, 0x14000
	v_add_u32_e32 v32, s77, v192
	v_add_u32_e32 v60, s79, v192
	ds_read_b128 v[16:19], v32
	ds_read_b128 v[20:23], v32 offset:1024
	ds_read_b128 v[24:27], v32 offset:2048
	ds_read_b128 v[32:35], v32 offset:3072
	ds_read_b128 v[48:51], v60
	ds_read_b128 v[52:55], v60 offset:1024
	ds_read_b128 v[56:59], v60 offset:2048
	ds_read_b128 v[60:63], v60 offset:3072
	s_add_i32 m0, s33, 0xc000
	ds_read_b128 v[160:163], v193
	ds_read_b128 v[164:167], v193 offset:1024
	ds_read_b128 v[180:183], v193 offset:2048
	ds_read_b128 v[184:187], v193 offset:3072
	ds_read_b128 v[188:191], v193 offset:4096
	ds_read_b128 v[194:197], v193 offset:5120
	ds_read_b128 v[198:201], v193 offset:6144
	ds_read_b128 v[202:205], v193 offset:7168
	global_load_lds_dwordx4 v176, s[6:7]
	s_add_i32 m0, s33, 0xe000
	s_nop 0
	global_load_lds_dwordx4 v178, s[6:7]
	s_waitcnt vmcnt(8)
	s_waitcnt lgkmcnt(0)
	s_barrier
	s_setprio 1
	s_waitcnt lgkmcnt(0)
	v_mfma_f32_16x16x32_bf16 v[156:159], v[16:19], v[160:163], v[156:159]
	v_mfma_f32_16x16x32_bf16 v[152:155], v[24:27], v[160:163], v[152:155]
	v_mfma_f32_16x16x32_bf16 v[140:143], v[16:19], v[180:183], v[140:143]
	v_mfma_f32_16x16x32_bf16 v[136:139], v[24:27], v[180:183], v[136:139]
	v_mfma_f32_16x16x32_bf16 v[124:127], v[16:19], v[188:191], v[124:127]
	v_mfma_f32_16x16x32_bf16 v[120:123], v[24:27], v[188:191], v[120:123]
	v_mfma_f32_16x16x32_bf16 v[108:111], v[16:19], v[198:201], v[108:111]
	v_mfma_f32_16x16x32_bf16 v[104:107], v[24:27], v[198:201], v[104:107]
	v_mfma_f32_16x16x32_bf16 v[156:159], v[20:23], v[164:167], v[156:159]
	v_mfma_f32_16x16x32_bf16 v[152:155], v[32:35], v[164:167], v[152:155]
	v_mfma_f32_16x16x32_bf16 v[140:143], v[20:23], v[184:187], v[140:143]
	v_mfma_f32_16x16x32_bf16 v[136:139], v[32:35], v[184:187], v[136:139]
	v_mfma_f32_16x16x32_bf16 v[124:127], v[20:23], v[194:197], v[124:127]
	v_mfma_f32_16x16x32_bf16 v[120:123], v[32:35], v[194:197], v[120:123]
	v_mfma_f32_16x16x32_bf16 v[108:111], v[20:23], v[202:205], v[108:111]
	v_mfma_f32_16x16x32_bf16 v[104:107], v[32:35], v[202:205], v[104:107]
	s_setprio 0
	s_setprio 1
	v_mfma_f32_16x16x32_bf16 v[148:151], v[48:51], v[160:163], v[148:151]
	v_mfma_f32_16x16x32_bf16 v[144:147], v[56:59], v[160:163], v[144:147]
	v_mfma_f32_16x16x32_bf16 v[132:135], v[48:51], v[180:183], v[132:135]
	v_mfma_f32_16x16x32_bf16 v[128:131], v[56:59], v[180:183], v[128:131]
	v_mfma_f32_16x16x32_bf16 v[116:119], v[48:51], v[188:191], v[116:119]
	v_mfma_f32_16x16x32_bf16 v[112:115], v[56:59], v[188:191], v[112:115]
	v_mfma_f32_16x16x32_bf16 v[100:103], v[48:51], v[198:201], v[100:103]
	v_mfma_f32_16x16x32_bf16 v[96:99], v[56:59], v[198:201], v[96:99]
	v_mfma_f32_16x16x32_bf16 v[148:151], v[52:55], v[164:167], v[148:151]
	v_mfma_f32_16x16x32_bf16 v[144:147], v[60:63], v[164:167], v[144:147]
	v_mfma_f32_16x16x32_bf16 v[132:135], v[52:55], v[184:187], v[132:135]
	v_mfma_f32_16x16x32_bf16 v[128:131], v[60:63], v[184:187], v[128:131]
	v_mfma_f32_16x16x32_bf16 v[116:119], v[52:55], v[194:197], v[116:119]
	v_mfma_f32_16x16x32_bf16 v[112:115], v[60:63], v[194:197], v[112:115]
	v_mfma_f32_16x16x32_bf16 v[100:103], v[52:55], v[202:205], v[100:103]
	v_mfma_f32_16x16x32_bf16 v[96:99], v[60:63], v[202:205], v[96:99]
	s_setprio 0
	s_barrier
	s_add_i32 s77, s77, s57
	s_mov_b32 m0, s77
	ds_read_b128 v[160:163], v193 offset:16384
	ds_read_b128 v[164:167], v193 offset:17408
	ds_read_b128 v[180:183], v193 offset:18432
	ds_read_b128 v[184:187], v193 offset:19456
	ds_read_b128 v[188:191], v193 offset:20480
	ds_read_b128 v[194:197], v193 offset:21504
	ds_read_b128 v[198:201], v193 offset:22528
	ds_read_b128 v[202:205], v193 offset:23552
	global_load_lds_dwordx4 v170, s[84:85]
	s_add_i32 m0, s77, 0x2000
	s_add_u32 s88, s84, 0x4000
	s_addc_u32 s89, s85, 0
	s_add_i32 s77, s79, s57
	global_load_lds_dwordx4 v174, s[84:85]
	s_mov_b32 m0, s77
	s_nop 0
	global_load_lds_dwordx4 v170, s[88:89]
	s_add_i32 m0, s77, 0x2000
	s_nop 0
	global_load_lds_dwordx4 v174, s[88:89]
	s_mov_b32 m0, s33
	s_nop 0
	global_load_lds_dwordx4 v168, s[86:87]
	s_mov_b32 m0, s42
	s_nop 0
	global_load_lds_dwordx4 v172, s[86:87]
	s_waitcnt vmcnt(8)
	s_waitcnt lgkmcnt(0)
	s_barrier
	s_setprio 1
	s_waitcnt lgkmcnt(0)
	v_mfma_f32_16x16x32_bf16 v[92:95], v[16:19], v[160:163], v[92:95]
	v_mfma_f32_16x16x32_bf16 v[88:91], v[24:27], v[160:163], v[88:91]
	v_mfma_f32_16x16x32_bf16 v[76:79], v[16:19], v[180:183], v[76:79]
	v_mfma_f32_16x16x32_bf16 v[72:75], v[24:27], v[180:183], v[72:75]
	v_mfma_f32_16x16x32_bf16 v[44:47], v[16:19], v[188:191], v[44:47]
	v_mfma_f32_16x16x32_bf16 v[40:43], v[24:27], v[188:191], v[40:43]
	v_mfma_f32_16x16x32_bf16 v[12:15], v[16:19], v[198:201], v[12:15]
	v_mfma_f32_16x16x32_bf16 v[8:11], v[24:27], v[198:201], v[8:11]
	v_mfma_f32_16x16x32_bf16 v[92:95], v[20:23], v[164:167], v[92:95]
	v_mfma_f32_16x16x32_bf16 v[88:91], v[32:35], v[164:167], v[88:91]
	v_mfma_f32_16x16x32_bf16 v[76:79], v[20:23], v[184:187], v[76:79]
	v_mfma_f32_16x16x32_bf16 v[72:75], v[32:35], v[184:187], v[72:75]
	v_mfma_f32_16x16x32_bf16 v[44:47], v[20:23], v[194:197], v[44:47]
	v_mfma_f32_16x16x32_bf16 v[40:43], v[32:35], v[194:197], v[40:43]
	v_mfma_f32_16x16x32_bf16 v[12:15], v[20:23], v[202:205], v[12:15]
	v_mfma_f32_16x16x32_bf16 v[8:11], v[32:35], v[202:205], v[8:11]
	s_setprio 0
	s_setprio 1
	v_mfma_f32_16x16x32_bf16 v[36:39], v[48:51], v[188:191], v[36:39]
	v_mfma_f32_16x16x32_bf16 v[28:31], v[56:59], v[188:191], v[28:31]
	v_mfma_f32_16x16x32_bf16 v[4:7], v[48:51], v[198:201], v[4:7]
	v_mfma_f32_16x16x32_bf16 v[0:3], v[56:59], v[198:201], v[0:3]
	v_mfma_f32_16x16x32_bf16 v[16:19], v[48:51], v[160:163], v[84:87]
	v_mfma_f32_16x16x32_bf16 v[20:23], v[56:59], v[160:163], v[80:83]
	v_mfma_f32_16x16x32_bf16 v[24:27], v[48:51], v[180:183], v[68:71]
	v_mfma_f32_16x16x32_bf16 v[32:35], v[56:59], v[180:183], v[64:67]
	v_mfma_f32_16x16x32_bf16 v[36:39], v[52:55], v[194:197], v[36:39]
	v_mfma_f32_16x16x32_bf16 v[28:31], v[60:63], v[194:197], v[28:31]
	v_mfma_f32_16x16x32_bf16 v[4:7], v[52:55], v[202:205], v[4:7]
	v_mfma_f32_16x16x32_bf16 v[0:3], v[60:63], v[202:205], v[0:3]
	v_mfma_f32_16x16x32_bf16 v[16:19], v[52:55], v[164:167], v[16:19]
	v_mfma_f32_16x16x32_bf16 v[20:23], v[60:63], v[164:167], v[20:23]
	v_mfma_f32_16x16x32_bf16 v[24:27], v[52:55], v[184:187], v[24:27]
	v_mfma_f32_16x16x32_bf16 v[32:35], v[60:63], v[184:187], v[32:35]
	s_setprio 0
	s_barrier
; #define PG8_STAGE(bufoff, gbase, voff) do { _Pragma("unroll") for (int _i = 0; _i < 2; ++_i) \
;         __builtin_amdgcn_global_load_lds((const unsigned*)((const char*)(gbase) + (voff)[_i]), (PG8_LAS unsigned*)(lds + (bufoff) + ldsw + _i * 8192), 16, 0, 0); } while (0)
; #define PG8_LDA(dst, b, h) do { _Pragma("unroll") for (int m = 0; m < 4; ++m) _Pragma("unroll") for (int k = 0; k < 2; ++k) dst[m][k] = *(const PG8_LAS bf16x8*)(lds + PG8_SA(b, h) + aoff + m * 2048 + k * 1024); } while (0)
; #define PG8_LDB(dst, b, h) do { _Pragma("unroll") for (int n = 0; n < 2; ++n) _Pragma("unroll") for (int k = 0; k < 2; ++k) dst[n][k] = *(const PG8_LAS bf16x8*)(lds + PG8_SB(b, h) + boff + n * 2048 + k * 1024); } while (0)
; #define PG8_MMA(ai, bj, At, Bt) do { __builtin_amdgcn_s_setprio(1); _Pragma("unroll") for (int m = 0; m < 4; ++m) _Pragma("unroll") for (int n = 0; n < 2; ++n) _Pragma("unroll") for (int k = 0; k < 2; ++k) \
;         acc[ai][bj][m][n] = __builtin_amdgcn_mfma_f32_16x16x32_bf16(Bt[n][k], At[m][k], acc[ai][bj][m][n], 0, 0, 0); __builtin_amdgcn_s_setprio(0); } while (0)
; #define PG8_WAIT_V(n) asm volatile("s_waitcnt vmcnt(" #n ")" ::: "memory")
; #define PG8_WAIT_L(n) asm volatile("s_waitcnt lgkmcnt(" #n ")" ::: "memory")
; #define PG8_BAR __builtin_amdgcn_s_barrier()
; #define PG8_SCHED __builtin_amdgcn_sched_barrier(0)
; template <class Epi, class Sched, bool ALIGN_EPI = false, bool SP2 = false>
; __device__ __forceinline__ void gemm_phase(PG8_LAS unsigned char* lds, const Gemm g, const Sched& S, const Epi& E) {
;     ...
;             PG8_WAIT_V(8); PG8_WAIT_L(0); PG8_BAR; PG8_MMA(1, 0, At, B0); PG8_MMA(1, 1, At, B1); PG8_BAR; PG8_SCHED;
;             PG8_LDB(B0, 1, 0); PG8_LDB(B1, 1, 1); PG8_SCHED; PG8_LDA(At, 1, 0); PG8_STAGE(PG8_SA(0, 1), a2 + hstep, voffA);
;             PG8_WAIT_V(8); PG8_WAIT_L(0); PG8_BAR; PG8_MMA(0, 0, At, B0); PG8_MMA(0, 1, At, B1); PG8_BAR; PG8_SCHED;
;             PG8_LDA(At, 1, 1); PG8_STAGE(PG8_SB(1, 0), b3, voffB); PG8_STAGE(PG8_SB(1, 1), b3 + hstep, voffB); PG8_STAGE(PG8_SA(1, 0), a3, voffA);
;             PG8_WAIT_V(8); PG8_WAIT_L(0); PG8_BAR; PG8_MMA(1, 0, At, B0); PG8_MMA(1, 1, At, B1); PG8_BAR; PG8_SCHED;
	s_add_i32 s77, 0, 0x18000
	s_add_i32 s79, 0, 0x1c000
	v_add_u32_e32 v60, s77, v192
	v_add_u32_e32 v64, s79, v192
	ds_read_b128 v[48:51], v60
	ds_read_b128 v[52:55], v60 offset:1024
	ds_read_b128 v[56:59], v60 offset:2048
	ds_read_b128 v[60:63], v60 offset:3072
	ds_read_b128 v[160:163], v64
	ds_read_b128 v[164:167], v64 offset:1024
	ds_read_b128 v[180:183], v64 offset:2048
	ds_read_b128 v[184:187], v64 offset:3072
	s_add_u32 s86, s86, 0x4000
	s_addc_u32 s87, s87, 0
	s_mov_b32 m0, s64
	ds_read_b128 v[64:67], v193 offset:32768
	ds_read_b128 v[68:71], v193 offset:33792
	ds_read_b128 v[80:83], v193 offset:34816
	ds_read_b128 v[84:87], v193 offset:35840
	ds_read_b128 v[188:191], v193 offset:36864
	ds_read_b128 v[194:197], v193 offset:37888
	ds_read_b128 v[198:201], v193 offset:38912
	ds_read_b128 v[202:205], v193 offset:39936
	global_load_lds_dwordx4 v168, s[86:87]
	s_mov_b32 m0, s65
	s_nop 0
	global_load_lds_dwordx4 v172, s[86:87]
	s_waitcnt vmcnt(8)
	s_waitcnt lgkmcnt(0)
	s_barrier
	s_setprio 1
	s_waitcnt lgkmcnt(0)
	v_mfma_f32_16x16x32_bf16 v[156:159], v[48:51], v[64:67], v[156:159]
	v_mfma_f32_16x16x32_bf16 v[152:155], v[56:59], v[64:67], v[152:155]
	v_mfma_f32_16x16x32_bf16 v[140:143], v[48:51], v[80:83], v[140:143]
	v_mfma_f32_16x16x32_bf16 v[136:139], v[56:59], v[80:83], v[136:139]
	v_mfma_f32_16x16x32_bf16 v[124:127], v[48:51], v[188:191], v[124:127]
	v_mfma_f32_16x16x32_bf16 v[120:123], v[56:59], v[188:191], v[120:123]
	v_mfma_f32_16x16x32_bf16 v[108:111], v[48:51], v[198:201], v[108:111]
	v_mfma_f32_16x16x32_bf16 v[104:107], v[56:59], v[198:201], v[104:107]
	v_mfma_f32_16x16x32_bf16 v[156:159], v[52:55], v[68:71], v[156:159]
	v_mfma_f32_16x16x32_bf16 v[152:155], v[60:63], v[68:71], v[152:155]
	v_mfma_f32_16x16x32_bf16 v[140:143], v[52:55], v[84:87], v[140:143]
	v_mfma_f32_16x16x32_bf16 v[136:139], v[60:63], v[84:87], v[136:139]
	v_mfma_f32_16x16x32_bf16 v[124:127], v[52:55], v[194:197], v[124:127]
	v_mfma_f32_16x16x32_bf16 v[120:123], v[60:63], v[194:197], v[120:123]
	v_mfma_f32_16x16x32_bf16 v[108:111], v[52:55], v[202:205], v[108:111]
	v_mfma_f32_16x16x32_bf16 v[104:107], v[60:63], v[202:205], v[104:107]
	s_setprio 0
	s_setprio 1
	v_mfma_f32_16x16x32_bf16 v[148:151], v[160:163], v[64:67], v[148:151]
	v_mfma_f32_16x16x32_bf16 v[64:67], v[180:183], v[64:67], v[144:147]
	v_mfma_f32_16x16x32_bf16 v[144:147], v[184:187], v[68:71], v[64:67]
	v_mfma_f32_16x16x32_bf16 v[64:67], v[160:163], v[80:83], v[132:135]
	v_mfma_f32_16x16x32_bf16 v[132:135], v[164:167], v[84:87], v[64:67]
	v_mfma_f32_16x16x32_bf16 v[64:67], v[180:183], v[80:83], v[128:131]
	v_mfma_f32_16x16x32_bf16 v[128:131], v[184:187], v[84:87], v[64:67]
	v_mfma_f32_16x16x32_bf16 v[64:67], v[160:163], v[188:191], v[116:119]
	v_mfma_f32_16x16x32_bf16 v[116:119], v[164:167], v[194:197], v[64:67]
	v_mfma_f32_16x16x32_bf16 v[64:67], v[180:183], v[188:191], v[112:115]
	v_mfma_f32_16x16x32_bf16 v[112:115], v[184:187], v[194:197], v[64:67]
	v_mfma_f32_16x16x32_bf16 v[64:67], v[160:163], v[198:201], v[100:103]
	v_mfma_f32_16x16x32_bf16 v[100:103], v[164:167], v[202:205], v[64:67]
	v_mfma_f32_16x16x32_bf16 v[64:67], v[180:183], v[198:201], v[96:99]
	v_mfma_f32_16x16x32_bf16 v[148:151], v[164:167], v[68:71], v[148:151]
	v_mfma_f32_16x16x32_bf16 v[96:99], v[184:187], v[202:205], v[64:67]
	s_setprio 0
	s_barrier
	s_add_u32 s86, s84, 0x8000
	s_addc_u32 s87, s85, 0
	s_add_i32 s77, s77, s57
	s_mov_b32 m0, s77
	ds_read_b128 v[64:67], v193 offset:49152
	ds_read_b128 v[68:71], v193 offset:50176
	ds_read_b128 v[188:191], v193 offset:51200
	ds_read_b128 v[194:197], v193 offset:52224
	ds_read_b128 v[198:201], v193 offset:53248
	ds_read_b128 v[202:205], v193 offset:54272
	ds_read_b128 v[206:209], v193 offset:55296
	ds_read_b128 v[210:213], v193 offset:56320
	global_load_lds_dwordx4 v170, s[86:87]
	s_add_i32 m0, s77, 0x2000
	s_add_u32 s84, s84, 0xc000
	s_addc_u32 s85, s85, 0
	s_add_i32 s77, s79, s57
	global_load_lds_dwordx4 v174, s[86:87]
	s_mov_b32 m0, s77
	s_nop 0
	global_load_lds_dwordx4 v170, s[84:85]
	s_add_i32 m0, s77, 0x2000
	s_nop 0
	global_load_lds_dwordx4 v174, s[84:85]
	s_mov_b32 m0, s53
	s_nop 0
	global_load_lds_dwordx4 v168, s[10:11]
	s_mov_b32 m0, s27
	s_nop 0
	global_load_lds_dwordx4 v172, s[10:11]
	s_waitcnt vmcnt(8)
	s_waitcnt lgkmcnt(0)
	s_barrier
	s_setprio 1
	s_waitcnt lgkmcnt(0)
	v_mfma_f32_16x16x32_bf16 v[80:83], v[48:51], v[64:67], v[92:95]
	v_mfma_f32_16x16x32_bf16 v[92:95], v[52:55], v[68:71], v[80:83]
	v_mfma_f32_16x16x32_bf16 v[80:83], v[56:59], v[64:67], v[88:91]
	v_mfma_f32_16x16x32_bf16 v[76:79], v[48:51], v[188:191], v[76:79]
	v_mfma_f32_16x16x32_bf16 v[72:75], v[56:59], v[188:191], v[72:75]
	v_mfma_f32_16x16x32_bf16 v[44:47], v[48:51], v[198:201], v[44:47]
	v_mfma_f32_16x16x32_bf16 v[40:43], v[56:59], v[198:201], v[40:43]
	v_mfma_f32_16x16x32_bf16 v[12:15], v[48:51], v[206:209], v[12:15]
	v_mfma_f32_16x16x32_bf16 v[8:11], v[56:59], v[206:209], v[8:11]
	v_mfma_f32_16x16x32_bf16 v[88:91], v[60:63], v[68:71], v[80:83]
	v_mfma_f32_16x16x32_bf16 v[76:79], v[52:55], v[194:197], v[76:79]
	v_mfma_f32_16x16x32_bf16 v[72:75], v[60:63], v[194:197], v[72:75]
	v_mfma_f32_16x16x32_bf16 v[44:47], v[52:55], v[202:205], v[44:47]
	v_mfma_f32_16x16x32_bf16 v[40:43], v[60:63], v[202:205], v[40:43]
	v_mfma_f32_16x16x32_bf16 v[12:15], v[52:55], v[210:213], v[12:15]
	v_mfma_f32_16x16x32_bf16 v[8:11], v[60:63], v[210:213], v[8:11]
	s_setprio 0
	s_setprio 1
	v_mfma_f32_16x16x32_bf16 v[16:19], v[160:163], v[64:67], v[16:19]
	v_mfma_f32_16x16x32_bf16 v[84:87], v[164:167], v[68:71], v[16:19]
	v_mfma_f32_16x16x32_bf16 v[16:19], v[180:183], v[64:67], v[20:23]
	v_mfma_f32_16x16x32_bf16 v[80:83], v[184:187], v[68:71], v[16:19]
	v_mfma_f32_16x16x32_bf16 v[16:19], v[160:163], v[188:191], v[24:27]
	v_mfma_f32_16x16x32_bf16 v[68:71], v[164:167], v[194:197], v[16:19]
	v_mfma_f32_16x16x32_bf16 v[16:19], v[180:183], v[188:191], v[32:35]
	v_mfma_f32_16x16x32_bf16 v[64:67], v[184:187], v[194:197], v[16:19]
	v_mfma_f32_16x16x32_bf16 v[16:19], v[160:163], v[198:201], v[36:39]
	v_mfma_f32_16x16x32_bf16 v[36:39], v[164:167], v[202:205], v[16:19]
	v_mfma_f32_16x16x32_bf16 v[16:19], v[180:183], v[198:201], v[28:31]
	v_mfma_f32_16x16x32_bf16 v[4:7], v[160:163], v[206:209], v[4:7]
	v_mfma_f32_16x16x32_bf16 v[0:3], v[180:183], v[206:209], v[0:3]
	v_mfma_f32_16x16x32_bf16 v[28:31], v[184:187], v[202:205], v[16:19]
	v_mfma_f32_16x16x32_bf16 v[4:7], v[164:167], v[210:213], v[4:7]
	v_mfma_f32_16x16x32_bf16 v[0:3], v[184:187], v[210:213], v[0:3]
	s_setprio 0
	s_barrier
	s_add_i32 s40, s40, 2
	s_add_u32 s6, s6, 0x10000
	s_addc_u32 s7, s7, 0
	s_add_u32 s30, s30, 0x10000
	s_addc_u32 s37, s37, 0
	s_cmp_gt_u32 s40, 13
	s_cbranch_scc0 .LBB0_1130
	s_and_b64 vcc, exec, s[70:71]
	s_cbranch_vccz .LBB0_1133
	s_barrier

; #define PG8_STAGE(bufoff, gbase, voff) do { _Pragma("unroll") for (int _i = 0; _i < 2; ++_i) \
;         __builtin_amdgcn_global_load_lds((const unsigned*)((const char*)(gbase) + (voff)[_i]), (PG8_LAS unsigned*)(lds + (bufoff) + ldsw + _i * 8192), 16, 0, 0); } while (0)
; #define PG8_WAIT_V(n) asm volatile("s_waitcnt vmcnt(" #n ")" ::: "memory")
; #define PG8_BAR __builtin_amdgcn_s_barrier()
;     __device__ void init(int M, int N, int G_, int c_) { base.init(M, N, G_, c_); }
; template <class Epi, class Sched, bool ALIGN_EPI = false, bool SP2 = false>
; __device__ __forceinline__ void gemm_phase(PG8_LAS unsigned char* lds, const Gemm g, const Sched& S, const Epi& E) {
;     ...
;         if (wr == 1) PG8_BAR;
;         PG8_WAIT_V(2); PG8_BAR;
;         PG8_STAGE(PG8_SB(1, 0), cB + kstep, voffB); PG8_STAGE(PG8_SA(1, 0), cA + kstep, voffA); PG8_STAGE(PG8_SB(1, 1), cB + hstep + kstep, voffB);
;         PG8_WAIT_V(6); PG8_BAR;
; __global__ void __launch_bounds__(NTHR, 2) trunk_fwd(Args args) {
;     ...
;             const u16* Aop = (const u16*)(ws + (ffn ? WS_ZA : WS_MG)); const u16* Bop = (const u16*)(wl + (s == 1 ? WO_2A : (s == 15 ? WO_2B : WO_OUT)));
;             const int Mr = ffn ? MROWS : MH, K = ffn ? FF : DM;
;             const float* x0 = nullptr;
;             pg8::Gemm g{Aop, Bop, Mr, DM, K}; pg8::StaticOrder S; S.init(Mr, DM, G, bx);
;             pg8::EpiResid E{x0, (u16*)(ws + WS_XB) + hrow * DM, (float*)(ws + WS_SSP) + hrow * 16, rep_ ? 0.0f : (ffn ? 0.5f : 1.0f)};
;             pg8::gemm_phase<pg8::EpiResid, pg8::StaticOrder, PG8_ALIGN, PG8_SP2>(lds, g, S, E);
.LBB0_1308:
	s_lshl_b64 s[8:9], s[56:57], 11
	s_add_u32 s8, s62, s8
	s_addc_u32 s9, s63, s9
	s_add_u32 s8, s8, 0x6400000
	s_addc_u32 s9, s9, 0
	s_lshl_b32 s10, s56, 6
	s_add_u32 s10, s62, s10
	s_addc_u32 s11, s63, 0
	s_add_u32 s10, s10, 0x1e500000
	s_addc_u32 s11, s11, 0
	s_and_b32 s52, s12, 3
	s_lshr_b32 s53, s3, 6
	s_lshl_b32 s54, s2, 6
	s_lshl_b32 s12, s2, 13
	s_lshl_b32 s55, s52, 5
	s_lshl_b32 s13, s52, 12
	s_add_u32 s2, s18, 0x8000
	v_mov_b32_e32 v187, v221
	s_addc_u32 s3, s19, 0
	s_add_i32 m0, s41, 0x18000
	v_lshl_add_u64 v[8:9], s[2:3], 0, v[186:187]
	v_mov_b32_e32 v191, v221
	s_waitcnt vmcnt(2)
	s_barrier
	global_load_lds_dwordx4 v[8:9], off
	s_add_i32 m0, s41, 0x1a000
	v_lshl_add_u64 v[8:9], s[2:3], 0, v[190:191]
	s_add_u32 s2, s16, 0x8000
	v_mov_b32_e32 v185, v221
	s_addc_u32 s3, s17, 0
	s_add_i32 s56, s41, 0x8000
	v_mov_b32_e32 v189, v221
	global_load_lds_dwordx4 v[8:9], off
	s_mov_b32 m0, s56
	s_add_i32 s57, s41, 0xa000
	global_load_lds_dwordx4 v184, s[2:3]
	v_lshl_add_u64 v[8:9], s[2:3], 0, v[188:189]
	s_add_u32 s2, s18, 0xc000
	s_mov_b32 m0, s57
	s_addc_u32 s3, s19, 0
	global_load_lds_dwordx4 v[8:9], off
	s_add_i32 m0, s41, 0x1c000
	s_nop 0
	global_load_lds_dwordx4 v186, s[2:3]
	s_add_i32 m0, s41, 0x1e000
	v_and_b32_e32 v7, 48, v0
	global_load_lds_dwordx4 v190, s[2:3]
	v_lshlrev_b32_e32 v8, 6, v0
	s_movk_i32 s2, 0x3c0
	v_lshlrev_b32_e32 v0, 2, v0
	v_and_or_b32 v7, v8, s2, v7
	v_and_b32_e32 v0, 32, v0
	v_bitop3_b32 v8, v7, s12, v0 bitop3:0xde
	v_bitop3_b32 v206, v7, s13, v0 bitop3:0xde
	v_lshlrev_b32_e32 v0, 10, v1
	v_and_b32_e32 v0, 0xfffff800, v0
	v_lshl_add_u32 v0, v2, 7, v0
	v_and_b32_e32 v1, 1, v1
	s_add_i32 s59, s53, -2
	v_lshl_or_b32 v0, v1, 6, v0
	s_cmpk_lt_u32 s5, 0x100
	v_lshl_add_u32 v194, v3, 1, v0
	v_lshlrev_b32_e32 v0, 10, v4
	s_cselect_b64 s[12:13], -1, 0
	s_and_b32 s61, s55, 32
	s_ashr_i32 s68, s60, 31
	s_ashr_i32 s69, s58, 31
	v_and_b32_e32 v0, 0xfffff800, v0
	v_cndmask_b32_e64 v192, 1.0, 0.5, s[0:1]
	s_waitcnt vmcnt(6)
	s_and_b64 s[0:1], s[0:1], exec
	v_lshl_add_u32 v0, v5, 7, v0
	v_and_b32_e32 v1, 1, v4
	s_cselect_b32 s70, 6, 5
	s_lshr_b32 s0, s22, 1
	v_lshl_or_b32 v0, v1, 6, v0
	s_mov_b32 s5, s31
	s_or_b32 s71, s0, 1
	v_mov_b32_e32 v193, v192
	v_mov_b32_e32 v195, v221
	v_lshl_add_u32 v196, v6, 1, v0
	v_mov_b32_e32 v197, v221
	s_mov_b32 s72, 0
	v_add_u32_e32 v207, 0, v8
	s_barrier
	s_branch .LBB0_1311

; #define PG8_STAGE(bufoff, gbase, voff) do { _Pragma("unroll") for (int _i = 0; _i < 2; ++_i) \
;         __builtin_amdgcn_global_load_lds((const unsigned*)((const char*)(gbase) + (voff)[_i]), (PG8_LAS unsigned*)(lds + (bufoff) + ldsw + _i * 8192), 16, 0, 0); } while (0)
; #define PG8_LDA(dst, b, h) do { _Pragma("unroll") for (int m = 0; m < 4; ++m) _Pragma("unroll") for (int k = 0; k < 2; ++k) dst[m][k] = *(const PG8_LAS bf16x8*)(lds + PG8_SA(b, h) + aoff + m * 2048 + k * 1024); } while (0)
; #define PG8_LDB(dst, b, h) do { _Pragma("unroll") for (int n = 0; n < 2; ++n) _Pragma("unroll") for (int k = 0; k < 2; ++k) dst[n][k] = *(const PG8_LAS bf16x8*)(lds + PG8_SB(b, h) + boff + n * 2048 + k * 1024); } while (0)
; #define PG8_MMA(ai, bj, At, Bt) do { __builtin_amdgcn_s_setprio(1); _Pragma("unroll") for (int m = 0; m < 4; ++m) _Pragma("unroll") for (int n = 0; n < 2; ++n) _Pragma("unroll") for (int k = 0; k < 2; ++k) \
;         acc[ai][bj][m][n] = __builtin_amdgcn_mfma_f32_16x16x32_bf16(Bt[n][k], At[m][k], acc[ai][bj][m][n], 0, 0, 0); __builtin_amdgcn_s_setprio(0); } while (0)
; #define PG8_WAIT_V(n) asm volatile("s_waitcnt vmcnt(" #n ")" ::: "memory")
; #define PG8_WAIT_L(n) asm volatile("s_waitcnt lgkmcnt(" #n ")" ::: "memory")
; #define PG8_BAR __builtin_amdgcn_s_barrier()
; #define PG8_SCHED __builtin_amdgcn_sched_barrier(0)
; template <class Epi, class Sched, bool ALIGN_EPI = false, bool SP2 = false>
; __device__ __forceinline__ void gemm_phase(PG8_LAS unsigned char* lds, const Gemm g, const Sched& S, const Epi& E) {
;     ...
;         for (int t = 0; t < nt; t += 2) {
;             const bool last = (t == nt - 2);
;             const char* a1 = cA + (size_t)(t + 1) * kstep;
;             const char* a2 = last ? nA : cA + (size_t)(t + 2) * kstep; const char* b2 = last ? nB : cB + (size_t)(t + 2) * kstep;
;             const char* a3 = a2 + kstep; const char* b3 = b2 + kstep;
;             if (last && has_next) S.a_ready(nxt);
;             if constexpr (SP2) {
;             PG8_LDB(B0, 0, 0); PG8_LDB(B1, 0, 1); PG8_SCHED; PG8_LDA(At, 0, 0); PG8_STAGE(PG8_SA(1, 1), a1 + hstep, voffA);
;             PG8_WAIT_V(8); PG8_WAIT_L(0); PG8_BAR; PG8_MMA(0, 0, At, B0); PG8_MMA(0, 1, At, B1); PG8_BAR; PG8_SCHED;
;             PG8_LDA(At, 0, 1); PG8_STAGE(PG8_SB(0, 0), b2, voffB); PG8_STAGE(PG8_SB(0, 1), b2 + hstep, voffB); PG8_STAGE(PG8_SA(0, 0), a2, voffA);
.LBB0_1322:
	s_add_i32 s75, s18, 2
	s_add_u32 s19, s16, 0x4000
	s_addc_u32 s20, s17, 0
	s_cmp_eq_u32 s59, s18
	s_cselect_b32 s64, s0, s19
	s_cselect_b32 s65, s1, s20
	s_cselect_b32 s20, s14, s66
	s_cselect_b32 s21, s15, s67
	s_add_u32 s18, s64, 0x8000
	s_addc_u32 s19, s65, 0
	s_add_i32 s76, 0, 0x10000
	s_add_i32 s78, 0, 0x14000
	v_add_u32_e32 v108, s76, v206
	v_add_u32_e32 v156, s78, v206
	ds_read_b128 v[80:83], v108
	ds_read_b128 v[84:87], v108 offset:1024
	ds_read_b128 v[104:107], v108 offset:2048
	ds_read_b128 v[108:111], v108 offset:3072
	ds_read_b128 v[128:131], v156
	ds_read_b128 v[136:139], v156 offset:1024
	ds_read_b128 v[152:155], v156 offset:2048
	ds_read_b128 v[156:159], v156 offset:3072
	s_add_i32 m0, s41, 0xc000
	ds_read_b128 v[160:163], v207
	ds_read_b128 v[164:167], v207 offset:1024
	ds_read_b128 v[168:171], v207 offset:2048
	ds_read_b128 v[172:175], v207 offset:3072
	ds_read_b128 v[176:179], v207 offset:4096
	ds_read_b128 v[180:183], v207 offset:5120
	ds_read_b128 v[198:201], v207 offset:6144
	ds_read_b128 v[202:205], v207 offset:7168
	global_load_lds_dwordx4 v194, s[16:17]
	s_add_i32 m0, s41, 0xe000
	s_nop 0
	global_load_lds_dwordx4 v196, s[16:17]
	s_waitcnt vmcnt(8)
	s_waitcnt lgkmcnt(0)
	s_barrier
	s_setprio 1
	s_waitcnt lgkmcnt(0)
	v_mfma_f32_16x16x32_bf16 v[148:151], v[80:83], v[160:163], v[148:151]
	v_mfma_f32_16x16x32_bf16 v[144:147], v[104:107], v[160:163], v[144:147]
	v_mfma_f32_16x16x32_bf16 v[124:127], v[80:83], v[168:171], v[124:127]
	v_mfma_f32_16x16x32_bf16 v[120:123], v[104:107], v[168:171], v[120:123]
	v_mfma_f32_16x16x32_bf16 v[100:103], v[80:83], v[176:179], v[100:103]
	v_mfma_f32_16x16x32_bf16 v[96:99], v[104:107], v[176:179], v[96:99]
	v_mfma_f32_16x16x32_bf16 v[76:79], v[80:83], v[198:201], v[76:79]
	v_mfma_f32_16x16x32_bf16 v[72:75], v[104:107], v[198:201], v[72:75]
	v_mfma_f32_16x16x32_bf16 v[148:151], v[84:87], v[164:167], v[148:151]
	v_mfma_f32_16x16x32_bf16 v[144:147], v[108:111], v[164:167], v[144:147]
	v_mfma_f32_16x16x32_bf16 v[124:127], v[84:87], v[172:175], v[124:127]
	v_mfma_f32_16x16x32_bf16 v[120:123], v[108:111], v[172:175], v[120:123]
	v_mfma_f32_16x16x32_bf16 v[100:103], v[84:87], v[180:183], v[100:103]
	v_mfma_f32_16x16x32_bf16 v[96:99], v[108:111], v[180:183], v[96:99]
	v_mfma_f32_16x16x32_bf16 v[76:79], v[84:87], v[202:205], v[76:79]
	v_mfma_f32_16x16x32_bf16 v[72:75], v[108:111], v[202:205], v[72:75]
	s_setprio 0
	s_setprio 1
	v_mfma_f32_16x16x32_bf16 v[140:143], v[128:131], v[160:163], v[140:143]
	v_mfma_f32_16x16x32_bf16 v[132:135], v[152:155], v[160:163], v[132:135]
	v_mfma_f32_16x16x32_bf16 v[116:119], v[128:131], v[168:171], v[116:119]
	v_mfma_f32_16x16x32_bf16 v[112:115], v[152:155], v[168:171], v[112:115]
	v_mfma_f32_16x16x32_bf16 v[92:95], v[128:131], v[176:179], v[92:95]
	v_mfma_f32_16x16x32_bf16 v[88:91], v[152:155], v[176:179], v[88:91]
	v_mfma_f32_16x16x32_bf16 v[68:71], v[128:131], v[198:201], v[68:71]
	v_mfma_f32_16x16x32_bf16 v[64:67], v[152:155], v[198:201], v[64:67]
	v_mfma_f32_16x16x32_bf16 v[140:143], v[136:139], v[164:167], v[140:143]
	v_mfma_f32_16x16x32_bf16 v[132:135], v[156:159], v[164:167], v[132:135]
	v_mfma_f32_16x16x32_bf16 v[116:119], v[136:139], v[172:175], v[116:119]
	v_mfma_f32_16x16x32_bf16 v[112:115], v[156:159], v[172:175], v[112:115]
	v_mfma_f32_16x16x32_bf16 v[92:95], v[136:139], v[180:183], v[92:95]
	v_mfma_f32_16x16x32_bf16 v[88:91], v[156:159], v[180:183], v[88:91]
	v_mfma_f32_16x16x32_bf16 v[68:71], v[136:139], v[202:205], v[68:71]
	v_mfma_f32_16x16x32_bf16 v[64:67], v[156:159], v[202:205], v[64:67]
	s_setprio 0
	s_barrier
	s_add_i32 s76, s76, s39
	s_mov_b32 m0, s76
	ds_read_b128 v[160:163], v207 offset:16384
	ds_read_b128 v[164:167], v207 offset:17408
	ds_read_b128 v[168:171], v207 offset:18432
	ds_read_b128 v[172:175], v207 offset:19456
	ds_read_b128 v[176:179], v207 offset:20480
	ds_read_b128 v[180:183], v207 offset:21504
	ds_read_b128 v[198:201], v207 offset:22528
	ds_read_b128 v[202:205], v207 offset:23552
	global_load_lds_dwordx4 v186, s[20:21]
	s_add_i32 m0, s76, 0x2000
	s_add_u32 s76, s20, 0x4000
	s_addc_u32 s77, s21, 0
	s_add_i32 s78, s78, s39
	global_load_lds_dwordx4 v190, s[20:21]
	s_mov_b32 m0, s78
	s_nop 0
	global_load_lds_dwordx4 v186, s[76:77]
	s_add_i32 m0, s78, 0x2000
	s_nop 0
	global_load_lds_dwordx4 v190, s[76:77]
	s_mov_b32 m0, s41
	s_nop 0
	global_load_lds_dwordx4 v184, s[64:65]
	s_mov_b32 m0, s42
	s_nop 0
	global_load_lds_dwordx4 v188, s[64:65]
	s_waitcnt vmcnt(8)
	s_waitcnt lgkmcnt(0)
	s_barrier
	s_setprio 1
	s_waitcnt lgkmcnt(0)
	v_mfma_f32_16x16x32_bf16 v[60:63], v[80:83], v[160:163], v[60:63]
	v_mfma_f32_16x16x32_bf16 v[56:59], v[104:107], v[160:163], v[56:59]
	v_mfma_f32_16x16x32_bf16 v[44:47], v[80:83], v[168:171], v[44:47]
	v_mfma_f32_16x16x32_bf16 v[40:43], v[104:107], v[168:171], v[40:43]
	v_mfma_f32_16x16x32_bf16 v[28:31], v[80:83], v[176:179], v[28:31]
	v_mfma_f32_16x16x32_bf16 v[24:27], v[104:107], v[176:179], v[24:27]
	v_mfma_f32_16x16x32_bf16 v[12:15], v[80:83], v[198:201], v[12:15]
	v_mfma_f32_16x16x32_bf16 v[8:11], v[104:107], v[198:201], v[8:11]
	v_mfma_f32_16x16x32_bf16 v[60:63], v[84:87], v[164:167], v[60:63]
	v_mfma_f32_16x16x32_bf16 v[56:59], v[108:111], v[164:167], v[56:59]
	v_mfma_f32_16x16x32_bf16 v[44:47], v[84:87], v[172:175], v[44:47]
	v_mfma_f32_16x16x32_bf16 v[40:43], v[108:111], v[172:175], v[40:43]
	v_mfma_f32_16x16x32_bf16 v[28:31], v[84:87], v[180:183], v[28:31]
	v_mfma_f32_16x16x32_bf16 v[24:27], v[108:111], v[180:183], v[24:27]
	v_mfma_f32_16x16x32_bf16 v[12:15], v[84:87], v[202:205], v[12:15]
	v_mfma_f32_16x16x32_bf16 v[8:11], v[108:111], v[202:205], v[8:11]
	s_setprio 0
	s_setprio 1
	v_mfma_f32_16x16x32_bf16 v[52:55], v[128:131], v[160:163], v[52:55]
	v_mfma_f32_16x16x32_bf16 v[48:51], v[152:155], v[160:163], v[48:51]
	v_mfma_f32_16x16x32_bf16 v[36:39], v[128:131], v[168:171], v[36:39]
	v_mfma_f32_16x16x32_bf16 v[32:35], v[152:155], v[168:171], v[32:35]
	v_mfma_f32_16x16x32_bf16 v[20:23], v[128:131], v[176:179], v[20:23]
	v_mfma_f32_16x16x32_bf16 v[16:19], v[152:155], v[176:179], v[16:19]
	v_mfma_f32_16x16x32_bf16 v[4:7], v[128:131], v[198:201], v[4:7]
	v_mfma_f32_16x16x32_bf16 v[0:3], v[152:155], v[198:201], v[0:3]
	v_mfma_f32_16x16x32_bf16 v[52:55], v[136:139], v[164:167], v[52:55]
	v_mfma_f32_16x16x32_bf16 v[48:51], v[156:159], v[164:167], v[48:51]
	v_mfma_f32_16x16x32_bf16 v[36:39], v[136:139], v[172:175], v[36:39]
	v_mfma_f32_16x16x32_bf16 v[32:35], v[156:159], v[172:175], v[32:35]
	v_mfma_f32_16x16x32_bf16 v[20:23], v[136:139], v[180:183], v[20:23]
	v_mfma_f32_16x16x32_bf16 v[16:19], v[156:159], v[180:183], v[16:19]
	v_mfma_f32_16x16x32_bf16 v[4:7], v[136:139], v[202:205], v[4:7]
	v_mfma_f32_16x16x32_bf16 v[0:3], v[156:159], v[202:205], v[0:3]
	s_setprio 0
	s_barrier
; #define PG8_STAGE(bufoff, gbase, voff) do { _Pragma("unroll") for (int _i = 0; _i < 2; ++_i) \
;         __builtin_amdgcn_global_load_lds((const unsigned*)((const char*)(gbase) + (voff)[_i]), (PG8_LAS unsigned*)(lds + (bufoff) + ldsw + _i * 8192), 16, 0, 0); } while (0)
; #define PG8_LDA(dst, b, h) do { _Pragma("unroll") for (int m = 0; m < 4; ++m) _Pragma("unroll") for (int k = 0; k < 2; ++k) dst[m][k] = *(const PG8_LAS bf16x8*)(lds + PG8_SA(b, h) + aoff + m * 2048 + k * 1024); } while (0)
; #define PG8_LDB(dst, b, h) do { _Pragma("unroll") for (int n = 0; n < 2; ++n) _Pragma("unroll") for (int k = 0; k < 2; ++k) dst[n][k] = *(const PG8_LAS bf16x8*)(lds + PG8_SB(b, h) + boff + n * 2048 + k * 1024); } while (0)
; #define PG8_MMA(ai, bj, At, Bt) do { __builtin_amdgcn_s_setprio(1); _Pragma("unroll") for (int m = 0; m < 4; ++m) _Pragma("unroll") for (int n = 0; n < 2; ++n) _Pragma("unroll") for (int k = 0; k < 2; ++k) \
;         acc[ai][bj][m][n] = __builtin_amdgcn_mfma_f32_16x16x32_bf16(Bt[n][k], At[m][k], acc[ai][bj][m][n], 0, 0, 0); __builtin_amdgcn_s_setprio(0); } while (0)
; #define PG8_WAIT_V(n) asm volatile("s_waitcnt vmcnt(" #n ")" ::: "memory")
; #define PG8_WAIT_L(n) asm volatile("s_waitcnt lgkmcnt(" #n ")" ::: "memory")
; #define PG8_BAR __builtin_amdgcn_s_barrier()
; #define PG8_SCHED __builtin_amdgcn_sched_barrier(0)
; template <class Epi, class Sched, bool ALIGN_EPI = false, bool SP2 = false>
; __device__ __forceinline__ void gemm_phase(PG8_LAS unsigned char* lds, const Gemm g, const Sched& S, const Epi& E) {
;     ...
;             PG8_WAIT_V(8); PG8_WAIT_L(0); PG8_BAR; PG8_MMA(1, 0, At, B0); PG8_MMA(1, 1, At, B1); PG8_BAR; PG8_SCHED;
;             PG8_LDB(B0, 1, 0); PG8_LDB(B1, 1, 1); PG8_SCHED; PG8_LDA(At, 1, 0); PG8_STAGE(PG8_SA(0, 1), a2 + hstep, voffA);
;             PG8_WAIT_V(8); PG8_WAIT_L(0); PG8_BAR; PG8_MMA(0, 0, At, B0); PG8_MMA(0, 1, At, B1); PG8_BAR; PG8_SCHED;
;             PG8_LDA(At, 1, 1); PG8_STAGE(PG8_SB(1, 0), b3, voffB); PG8_STAGE(PG8_SB(1, 1), b3 + hstep, voffB); PG8_STAGE(PG8_SA(1, 0), a3, voffA);
;             PG8_WAIT_V(8); PG8_WAIT_L(0); PG8_BAR; PG8_MMA(1, 0, At, B0); PG8_MMA(1, 1, At, B1); PG8_BAR; PG8_SCHED;
	s_add_i32 s76, 0, 0x18000
	s_add_i32 s77, 0, 0x1c000
	v_add_u32_e32 v108, s76, v206
	v_add_u32_e32 v156, s77, v206
	ds_read_b128 v[80:83], v108
	ds_read_b128 v[84:87], v108 offset:1024
	ds_read_b128 v[104:107], v108 offset:2048
	ds_read_b128 v[108:111], v108 offset:3072
	ds_read_b128 v[128:131], v156
	ds_read_b128 v[136:139], v156 offset:1024
	ds_read_b128 v[152:155], v156 offset:2048
	ds_read_b128 v[156:159], v156 offset:3072
	s_add_u32 s64, s64, 0x4000
	s_addc_u32 s65, s65, 0
	s_mov_b32 m0, s50
	ds_read_b128 v[160:163], v207 offset:32768
	ds_read_b128 v[164:167], v207 offset:33792
	ds_read_b128 v[168:171], v207 offset:34816
	ds_read_b128 v[172:175], v207 offset:35840
	ds_read_b128 v[176:179], v207 offset:36864
	ds_read_b128 v[180:183], v207 offset:37888
	ds_read_b128 v[198:201], v207 offset:38912
	ds_read_b128 v[202:205], v207 offset:39936
	global_load_lds_dwordx4 v184, s[64:65]
	s_mov_b32 m0, s51
	s_nop 0
	global_load_lds_dwordx4 v188, s[64:65]
	s_waitcnt vmcnt(8)
	s_waitcnt lgkmcnt(0)
	s_barrier
	s_setprio 1
	s_waitcnt lgkmcnt(0)
	v_mfma_f32_16x16x32_bf16 v[148:151], v[80:83], v[160:163], v[148:151]
	v_mfma_f32_16x16x32_bf16 v[144:147], v[104:107], v[160:163], v[144:147]
	v_mfma_f32_16x16x32_bf16 v[124:127], v[80:83], v[168:171], v[124:127]
	v_mfma_f32_16x16x32_bf16 v[120:123], v[104:107], v[168:171], v[120:123]
	v_mfma_f32_16x16x32_bf16 v[100:103], v[80:83], v[176:179], v[100:103]
	v_mfma_f32_16x16x32_bf16 v[96:99], v[104:107], v[176:179], v[96:99]
	v_mfma_f32_16x16x32_bf16 v[76:79], v[80:83], v[198:201], v[76:79]
	v_mfma_f32_16x16x32_bf16 v[72:75], v[104:107], v[198:201], v[72:75]
	v_mfma_f32_16x16x32_bf16 v[148:151], v[84:87], v[164:167], v[148:151]
	v_mfma_f32_16x16x32_bf16 v[144:147], v[108:111], v[164:167], v[144:147]
	v_mfma_f32_16x16x32_bf16 v[124:127], v[84:87], v[172:175], v[124:127]
	v_mfma_f32_16x16x32_bf16 v[120:123], v[108:111], v[172:175], v[120:123]
	v_mfma_f32_16x16x32_bf16 v[100:103], v[84:87], v[180:183], v[100:103]
	v_mfma_f32_16x16x32_bf16 v[96:99], v[108:111], v[180:183], v[96:99]
	v_mfma_f32_16x16x32_bf16 v[76:79], v[84:87], v[202:205], v[76:79]
	v_mfma_f32_16x16x32_bf16 v[72:75], v[108:111], v[202:205], v[72:75]
	s_setprio 0
	s_setprio 1
	v_mfma_f32_16x16x32_bf16 v[140:143], v[128:131], v[160:163], v[140:143]
	v_mfma_f32_16x16x32_bf16 v[132:135], v[152:155], v[160:163], v[132:135]
	v_mfma_f32_16x16x32_bf16 v[116:119], v[128:131], v[168:171], v[116:119]
	v_mfma_f32_16x16x32_bf16 v[112:115], v[152:155], v[168:171], v[112:115]
	v_mfma_f32_16x16x32_bf16 v[92:95], v[128:131], v[176:179], v[92:95]
	v_mfma_f32_16x16x32_bf16 v[88:91], v[152:155], v[176:179], v[88:91]
	v_mfma_f32_16x16x32_bf16 v[68:71], v[128:131], v[198:201], v[68:71]
	v_mfma_f32_16x16x32_bf16 v[64:67], v[152:155], v[198:201], v[64:67]
	v_mfma_f32_16x16x32_bf16 v[140:143], v[136:139], v[164:167], v[140:143]
	v_mfma_f32_16x16x32_bf16 v[132:135], v[156:159], v[164:167], v[132:135]
	v_mfma_f32_16x16x32_bf16 v[116:119], v[136:139], v[172:175], v[116:119]
	v_mfma_f32_16x16x32_bf16 v[112:115], v[156:159], v[172:175], v[112:115]
	v_mfma_f32_16x16x32_bf16 v[92:95], v[136:139], v[180:183], v[92:95]
	v_mfma_f32_16x16x32_bf16 v[88:91], v[156:159], v[180:183], v[88:91]
	v_mfma_f32_16x16x32_bf16 v[68:71], v[136:139], v[202:205], v[68:71]
	v_mfma_f32_16x16x32_bf16 v[64:67], v[156:159], v[202:205], v[64:67]
	s_setprio 0
	s_barrier
	s_add_u32 s64, s20, 0x8000
	s_addc_u32 s65, s21, 0
	s_add_i32 s76, s76, s39
	s_mov_b32 m0, s76
	ds_read_b128 v[160:163], v207 offset:49152
	ds_read_b128 v[164:167], v207 offset:50176
	ds_read_b128 v[168:171], v207 offset:51200
	ds_read_b128 v[172:175], v207 offset:52224
	ds_read_b128 v[176:179], v207 offset:53248
	ds_read_b128 v[180:183], v207 offset:54272
	ds_read_b128 v[198:201], v207 offset:55296
	ds_read_b128 v[202:205], v207 offset:56320
	global_load_lds_dwordx4 v186, s[64:65]
	s_add_i32 m0, s76, 0x2000
	s_add_u32 s20, s20, 0xc000
	v_lshl_add_u64 v[208:209], s[64:65], 0, v[190:191]
	s_addc_u32 s21, s21, 0
	s_add_i32 s64, s77, s39
	global_load_lds_dwordx4 v[208:209], off
	s_mov_b32 m0, s64
	s_nop 0
	global_load_lds_dwordx4 v186, s[20:21]
	s_add_i32 m0, s64, 0x2000
	s_nop 0
	global_load_lds_dwordx4 v190, s[20:21]
	s_mov_b32 m0, s56
	s_nop 0
	global_load_lds_dwordx4 v184, s[18:19]
	s_mov_b32 m0, s57
	s_nop 0
	global_load_lds_dwordx4 v188, s[18:19]
	s_waitcnt vmcnt(8)
	s_waitcnt lgkmcnt(0)
	s_barrier
	s_setprio 1
	s_waitcnt lgkmcnt(0)
	v_mfma_f32_16x16x32_bf16 v[60:63], v[80:83], v[160:163], v[60:63]
	v_mfma_f32_16x16x32_bf16 v[56:59], v[104:107], v[160:163], v[56:59]
	v_mfma_f32_16x16x32_bf16 v[44:47], v[80:83], v[168:171], v[44:47]
	v_mfma_f32_16x16x32_bf16 v[40:43], v[104:107], v[168:171], v[40:43]
	v_mfma_f32_16x16x32_bf16 v[28:31], v[80:83], v[176:179], v[28:31]
	v_mfma_f32_16x16x32_bf16 v[24:27], v[104:107], v[176:179], v[24:27]
	v_mfma_f32_16x16x32_bf16 v[12:15], v[80:83], v[198:201], v[12:15]
	v_mfma_f32_16x16x32_bf16 v[8:11], v[104:107], v[198:201], v[8:11]
	v_mfma_f32_16x16x32_bf16 v[60:63], v[84:87], v[164:167], v[60:63]
	v_mfma_f32_16x16x32_bf16 v[56:59], v[108:111], v[164:167], v[56:59]
	v_mfma_f32_16x16x32_bf16 v[44:47], v[84:87], v[172:175], v[44:47]
	v_mfma_f32_16x16x32_bf16 v[40:43], v[108:111], v[172:175], v[40:43]
	v_mfma_f32_16x16x32_bf16 v[28:31], v[84:87], v[180:183], v[28:31]
	v_mfma_f32_16x16x32_bf16 v[24:27], v[108:111], v[180:183], v[24:27]
	v_mfma_f32_16x16x32_bf16 v[12:15], v[84:87], v[202:205], v[12:15]
	v_mfma_f32_16x16x32_bf16 v[8:11], v[108:111], v[202:205], v[8:11]
	s_setprio 0
	s_setprio 1
	v_mfma_f32_16x16x32_bf16 v[52:55], v[128:131], v[160:163], v[52:55]
	v_mfma_f32_16x16x32_bf16 v[48:51], v[152:155], v[160:163], v[48:51]
	v_mfma_f32_16x16x32_bf16 v[36:39], v[128:131], v[168:171], v[36:39]
	v_mfma_f32_16x16x32_bf16 v[32:35], v[152:155], v[168:171], v[32:35]
	v_mfma_f32_16x16x32_bf16 v[20:23], v[128:131], v[176:179], v[20:23]
	v_mfma_f32_16x16x32_bf16 v[16:19], v[152:155], v[176:179], v[16:19]
	v_mfma_f32_16x16x32_bf16 v[4:7], v[128:131], v[198:201], v[4:7]
	v_mfma_f32_16x16x32_bf16 v[0:3], v[152:155], v[198:201], v[0:3]
	v_mfma_f32_16x16x32_bf16 v[52:55], v[136:139], v[164:167], v[52:55]
	v_mfma_f32_16x16x32_bf16 v[48:51], v[156:159], v[164:167], v[48:51]
	v_mfma_f32_16x16x32_bf16 v[36:39], v[136:139], v[172:175], v[36:39]
	v_mfma_f32_16x16x32_bf16 v[32:35], v[156:159], v[172:175], v[32:35]
	v_mfma_f32_16x16x32_bf16 v[20:23], v[136:139], v[180:183], v[20:23]
	v_mfma_f32_16x16x32_bf16 v[16:19], v[156:159], v[180:183], v[16:19]
	v_mfma_f32_16x16x32_bf16 v[4:7], v[136:139], v[202:205], v[4:7]
	v_mfma_f32_16x16x32_bf16 v[0:3], v[156:159], v[202:205], v[0:3]
	s_setprio 0
	s_barrier
	s_add_u32 s16, s16, 0x10000
	s_addc_u32 s17, s17, 0
	s_add_u32 s66, s66, 0x10000
	s_addc_u32 s67, s67, 0
	s_cmp_ge_u32 s75, s53
	s_mov_b32 s18, s75
	s_cbranch_scc0 .LBB0_1322
	s_and_b64 vcc, exec, s[12:13]
	s_cbranch_vccz .LBB0_1325
	s_barrier

; #define PG8_STAGE(bufoff, gbase, voff) do { _Pragma("unroll") for (int _i = 0; _i < 2; ++_i) \
;         __builtin_amdgcn_global_load_lds((const unsigned*)((const char*)(gbase) + (voff)[_i]), (PG8_LAS unsigned*)(lds + (bufoff) + ldsw + _i * 8192), 16, 0, 0); } while (0)
; #define PG8_WAIT_V(n) asm volatile("s_waitcnt vmcnt(" #n ")" ::: "memory")
; #define PG8_BAR __builtin_amdgcn_s_barrier()
;     __device__ void init(int M, int N, int G_, int c_) { base.init(M, N, G_, c_); }
; template <class Epi, class Sched, bool ALIGN_EPI = false, bool SP2 = false>
; __device__ __forceinline__ void gemm_phase(PG8_LAS unsigned char* lds, const Gemm g, const Sched& S, const Epi& E) {
;     ...
;         if (wr == 1) PG8_BAR;
;         PG8_WAIT_V(2); PG8_BAR;
;         PG8_STAGE(PG8_SB(1, 0), cB + kstep, voffB); PG8_STAGE(PG8_SA(1, 0), cA + kstep, voffA); PG8_STAGE(PG8_SB(1, 1), cB + hstep + kstep, voffB);
;         PG8_WAIT_V(6); PG8_BAR;
; __global__ void __launch_bounds__(NTHR, 2) trunk_fwd(Args args) {
;     ...
;             pg8::Gemm g{(const u16*)(ws + WS_XB), (const u16*)(wl + (s == 0 ? WO_13A : WO_13B)), MROWS, 2 * FF, DM}; pg8::StaticOrder S; S.init(MROWS, 2 * FF, G, bx);
;             pg8::EpiSwiglu E{(u16*)(ws + WS_ZA), (const float*)(ws + WS_SSP)};
;             pg8::gemm_phase<pg8::EpiSwiglu, pg8::StaticOrder, PG8_ALIGN, PG8_SP2>(lds, g, S, E);
.LBB0_1350:
	s_add_u32 s50, s62, 0xa400000
	s_addc_u32 s51, s63, 0
	s_add_u32 s4, s62, 0x1e500000
	s_addc_u32 s5, s63, 0
	s_lshl_b32 s9, s6, 5
	s_and_b32 s53, s9, 0x60
	s_lshl_b32 s52, s7, 6
	s_lshl_b32 s8, s7, 13
	s_lshl_b32 s10, s53, 7
	s_add_u32 s6, s20, 0x8000
	v_mov_b32_e32 v149, v221
	s_addc_u32 s7, s21, 0
	s_add_i32 m0, s37, 0x18000
	v_lshl_add_u64 v[8:9], s[6:7], 0, v[148:149]
	v_mov_b32_e32 v145, v221
	s_waitcnt vmcnt(2)
	s_barrier
	global_load_lds_dwordx4 v[8:9], off
	s_add_i32 m0, s37, 0x1a000
	v_lshl_add_u64 v[8:9], s[6:7], 0, v[144:145]
	s_add_u32 s6, s18, 0x8000
	v_mov_b32_e32 v151, v221
	s_addc_u32 s7, s19, 0
	s_add_i32 s54, s37, 0x8000
	v_mov_b32_e32 v147, v221
	global_load_lds_dwordx4 v[8:9], off
	s_mov_b32 m0, s54
	s_add_i32 s55, s37, 0xa000
	global_load_lds_dwordx4 v150, s[6:7]
	v_lshl_add_u64 v[8:9], s[6:7], 0, v[146:147]
	s_add_u32 s6, s20, 0xc000
	s_mov_b32 m0, s55
	s_addc_u32 s7, s21, 0
	global_load_lds_dwordx4 v[8:9], off
	s_add_i32 m0, s37, 0x1c000
	s_nop 0
	global_load_lds_dwordx4 v148, s[6:7]
	s_add_i32 m0, s37, 0x1e000
	s_sext_i32_i16 s17, s2
	global_load_lds_dwordx4 v144, s[6:7]
	v_and_b32_e32 v7, 48, v0
	v_lshlrev_b32_e32 v8, 6, v0
	s_movk_i32 s2, 0x3c0
	v_lshlrev_b32_e32 v0, 2, v0
	v_and_or_b32 v7, v8, s2, v7
	v_and_b32_e32 v0, 32, v0
	v_bitop3_b32 v8, v7, s8, v0 bitop3:0xde
	v_bitop3_b32 v162, s10, v7, v0 bitop3:0xf6
	v_lshlrev_b32_e32 v0, 10, v5
	v_and_b32_e32 v0, 0xfffff800, v0
	v_lshl_add_u32 v0, v4, 7, v0
	v_and_b32_e32 v4, 1, v5
	v_lshl_or_b32 v0, v4, 6, v0
	v_lshl_add_u32 v152, v6, 1, v0
	v_lshlrev_b32_e32 v0, 10, v1
	v_and_b32_e32 v0, 0xfffff800, v0
	s_waitcnt vmcnt(6)
	v_lshl_add_u32 v0, v2, 7, v0
	v_and_b32_e32 v1, 1, v1
	s_cmpk_lt_u32 s3, 0x100
	v_lshl_or_b32 v0, v1, 6, v0
	s_cselect_b64 s[6:7], -1, 0
	s_and_b32 s56, s9, 32
	s_ashr_i32 s57, s60, 31
	v_mov_b32_e32 v153, v221
	v_lshl_add_u32 v154, v3, 1, v0
	v_mov_b32_e32 v155, v221
	s_mov_b32 s59, 0
	v_add_u32_e32 v163, 0, v8
	s_mov_b32 s74, 0x3a800000
	s_barrier
	s_branch .LBB0_1353

; #define PG8_STAGE(bufoff, gbase, voff) do { _Pragma("unroll") for (int _i = 0; _i < 2; ++_i) \
;         __builtin_amdgcn_global_load_lds((const unsigned*)((const char*)(gbase) + (voff)[_i]), (PG8_LAS unsigned*)(lds + (bufoff) + ldsw + _i * 8192), 16, 0, 0); } while (0)
; #define PG8_LDA(dst, b, h) do { _Pragma("unroll") for (int m = 0; m < 4; ++m) _Pragma("unroll") for (int k = 0; k < 2; ++k) dst[m][k] = *(const PG8_LAS bf16x8*)(lds + PG8_SA(b, h) + aoff + m * 2048 + k * 1024); } while (0)
; #define PG8_LDB(dst, b, h) do { _Pragma("unroll") for (int n = 0; n < 2; ++n) _Pragma("unroll") for (int k = 0; k < 2; ++k) dst[n][k] = *(const PG8_LAS bf16x8*)(lds + PG8_SB(b, h) + boff + n * 2048 + k * 1024); } while (0)
; #define PG8_MMA(ai, bj, At, Bt) do { __builtin_amdgcn_s_setprio(1); _Pragma("unroll") for (int m = 0; m < 4; ++m) _Pragma("unroll") for (int n = 0; n < 2; ++n) _Pragma("unroll") for (int k = 0; k < 2; ++k) \
;         acc[ai][bj][m][n] = __builtin_amdgcn_mfma_f32_16x16x32_bf16(Bt[n][k], At[m][k], acc[ai][bj][m][n], 0, 0, 0); __builtin_amdgcn_s_setprio(0); } while (0)
; #define PG8_WAIT_V(n) asm volatile("s_waitcnt vmcnt(" #n ")" ::: "memory")
; #define PG8_WAIT_L(n) asm volatile("s_waitcnt lgkmcnt(" #n ")" ::: "memory")
; #define PG8_BAR __builtin_amdgcn_s_barrier()
; #define PG8_SCHED __builtin_amdgcn_sched_barrier(0)
; template <class Epi, class Sched, bool ALIGN_EPI = false, bool SP2 = false>
; __device__ __forceinline__ void gemm_phase(PG8_LAS unsigned char* lds, const Gemm g, const Sched& S, const Epi& E) {
;     ...
;         for (int t = 0; t < nt; t += 2) {
;             const bool last = (t == nt - 2);
;             const char* a1 = cA + (size_t)(t + 1) * kstep;
;             const char* a2 = last ? nA : cA + (size_t)(t + 2) * kstep; const char* b2 = last ? nB : cB + (size_t)(t + 2) * kstep;
;             const char* a3 = a2 + kstep; const char* b3 = b2 + kstep;
;             if (last && has_next) S.a_ready(nxt);
;             if constexpr (SP2) {
;             PG8_LDB(B0, 0, 0); PG8_LDB(B1, 0, 1); PG8_SCHED; PG8_LDA(At, 0, 0); PG8_STAGE(PG8_SA(1, 1), a1 + hstep, voffA);
;             PG8_WAIT_V(8); PG8_WAIT_L(0); PG8_BAR; PG8_MMA(0, 0, At, B0); PG8_MMA(0, 1, At, B1); PG8_BAR; PG8_SCHED;
;             PG8_LDA(At, 0, 1); PG8_STAGE(PG8_SB(0, 0), b2, voffB); PG8_STAGE(PG8_SB(0, 1), b2 + hstep, voffB); PG8_STAGE(PG8_SA(0, 0), a2, voffA);
.LBB0_1356:
	s_add_u32 s20, s18, 0x4000
	s_addc_u32 s21, s19, 0
	s_cmp_eq_u32 s68, 12
	s_cselect_b32 s64, s40, s20
	s_cselect_b32 s65, s11, s21
	s_cselect_b32 s62, s61, s66
	s_cselect_b32 s63, s9, s67
	s_add_u32 s20, s64, 0x8000
	s_addc_u32 s21, s65, 0
	s_add_i32 s69, 0, 0x10000
	s_add_i32 s72, 0, 0x14000
	v_add_u32_e32 v140, s69, v162
	v_add_u32_e32 v160, s72, v162
	ds_read_b128 v[128:131], v140
	ds_read_b128 v[132:135], v140 offset:1024
	ds_read_b128 v[136:139], v140 offset:2048
	ds_read_b128 v[140:143], v140 offset:3072
	ds_read_b128 v[156:159], v160
	ds_read_b128 v[164:167], v160 offset:1024
	ds_read_b128 v[168:171], v160 offset:2048
	ds_read_b128 v[172:175], v160 offset:3072
	s_add_i32 m0, s37, 0xc000
	ds_read_b128 v[176:179], v163
	ds_read_b128 v[180:183], v163 offset:1024
	ds_read_b128 v[184:187], v163 offset:2048
	ds_read_b128 v[188:191], v163 offset:3072
	ds_read_b128 v[192:195], v163 offset:4096
	ds_read_b128 v[196:199], v163 offset:5120
	ds_read_b128 v[200:203], v163 offset:6144
	ds_read_b128 v[204:207], v163 offset:7168
	global_load_lds_dwordx4 v152, s[18:19]
	s_add_i32 m0, s37, 0xe000
	s_nop 0
	global_load_lds_dwordx4 v154, s[18:19]
	s_waitcnt vmcnt(8)
	s_waitcnt lgkmcnt(0)
	s_barrier
	s_setprio 1
	s_waitcnt lgkmcnt(0)
	v_mfma_f32_16x16x32_bf16 v[124:127], v[128:131], v[176:179], v[124:127]
	v_mfma_f32_16x16x32_bf16 v[120:123], v[136:139], v[176:179], v[120:123]
	v_mfma_f32_16x16x32_bf16 v[108:111], v[128:131], v[184:187], v[108:111]
	v_mfma_f32_16x16x32_bf16 v[104:107], v[136:139], v[184:187], v[104:107]
	v_mfma_f32_16x16x32_bf16 v[92:95], v[128:131], v[192:195], v[92:95]
	v_mfma_f32_16x16x32_bf16 v[88:91], v[136:139], v[192:195], v[88:91]
	v_mfma_f32_16x16x32_bf16 v[76:79], v[128:131], v[200:203], v[76:79]
	v_mfma_f32_16x16x32_bf16 v[72:75], v[136:139], v[200:203], v[72:75]
	v_mfma_f32_16x16x32_bf16 v[124:127], v[132:135], v[180:183], v[124:127]
	v_mfma_f32_16x16x32_bf16 v[120:123], v[140:143], v[180:183], v[120:123]
	v_mfma_f32_16x16x32_bf16 v[108:111], v[132:135], v[188:191], v[108:111]
	v_mfma_f32_16x16x32_bf16 v[104:107], v[140:143], v[188:191], v[104:107]
	v_mfma_f32_16x16x32_bf16 v[92:95], v[132:135], v[196:199], v[92:95]
	v_mfma_f32_16x16x32_bf16 v[88:91], v[140:143], v[196:199], v[88:91]
	v_mfma_f32_16x16x32_bf16 v[76:79], v[132:135], v[204:207], v[76:79]
	v_mfma_f32_16x16x32_bf16 v[72:75], v[140:143], v[204:207], v[72:75]
	s_setprio 0
	s_setprio 1
	v_mfma_f32_16x16x32_bf16 v[116:119], v[156:159], v[176:179], v[116:119]
	v_mfma_f32_16x16x32_bf16 v[112:115], v[168:171], v[176:179], v[112:115]
	v_mfma_f32_16x16x32_bf16 v[100:103], v[156:159], v[184:187], v[100:103]
	v_mfma_f32_16x16x32_bf16 v[96:99], v[168:171], v[184:187], v[96:99]
	v_mfma_f32_16x16x32_bf16 v[84:87], v[156:159], v[192:195], v[84:87]
	v_mfma_f32_16x16x32_bf16 v[80:83], v[168:171], v[192:195], v[80:83]
	v_mfma_f32_16x16x32_bf16 v[68:71], v[156:159], v[200:203], v[68:71]
	v_mfma_f32_16x16x32_bf16 v[64:67], v[168:171], v[200:203], v[64:67]
	v_mfma_f32_16x16x32_bf16 v[116:119], v[164:167], v[180:183], v[116:119]
	v_mfma_f32_16x16x32_bf16 v[112:115], v[172:175], v[180:183], v[112:115]
	v_mfma_f32_16x16x32_bf16 v[100:103], v[164:167], v[188:191], v[100:103]
	v_mfma_f32_16x16x32_bf16 v[96:99], v[172:175], v[188:191], v[96:99]
	v_mfma_f32_16x16x32_bf16 v[84:87], v[164:167], v[196:199], v[84:87]
	v_mfma_f32_16x16x32_bf16 v[80:83], v[172:175], v[196:199], v[80:83]
	v_mfma_f32_16x16x32_bf16 v[68:71], v[164:167], v[204:207], v[68:71]
	v_mfma_f32_16x16x32_bf16 v[64:67], v[172:175], v[204:207], v[64:67]
	s_setprio 0
	s_barrier
	s_add_i32 s69, s69, s30
	s_mov_b32 m0, s69
	ds_read_b128 v[176:179], v163 offset:16384
	ds_read_b128 v[180:183], v163 offset:17408
	ds_read_b128 v[184:187], v163 offset:18432
	ds_read_b128 v[188:191], v163 offset:19456
	ds_read_b128 v[192:195], v163 offset:20480
	ds_read_b128 v[196:199], v163 offset:21504
	ds_read_b128 v[200:203], v163 offset:22528
	ds_read_b128 v[204:207], v163 offset:23552
	global_load_lds_dwordx4 v148, s[62:63]
	s_add_i32 m0, s69, 0x2000
	s_add_u32 s70, s62, 0x4000
	s_addc_u32 s71, s63, 0
	s_add_i32 s69, s72, s30
	global_load_lds_dwordx4 v144, s[62:63]
	s_mov_b32 m0, s69
	s_nop 0
	global_load_lds_dwordx4 v148, s[70:71]
	s_add_i32 m0, s69, 0x2000
	s_nop 0
	global_load_lds_dwordx4 v144, s[70:71]
	s_mov_b32 m0, s37
	s_nop 0
	global_load_lds_dwordx4 v150, s[64:65]
	s_mov_b32 m0, s39
	s_nop 0
	global_load_lds_dwordx4 v146, s[64:65]
	s_waitcnt vmcnt(8)
	s_waitcnt lgkmcnt(0)
	s_barrier
	s_setprio 1
	s_waitcnt lgkmcnt(0)
	v_mfma_f32_16x16x32_bf16 v[60:63], v[128:131], v[176:179], v[60:63]
	v_mfma_f32_16x16x32_bf16 v[56:59], v[136:139], v[176:179], v[56:59]
	v_mfma_f32_16x16x32_bf16 v[44:47], v[128:131], v[184:187], v[44:47]
	v_mfma_f32_16x16x32_bf16 v[40:43], v[136:139], v[184:187], v[40:43]
	v_mfma_f32_16x16x32_bf16 v[28:31], v[128:131], v[192:195], v[28:31]
	v_mfma_f32_16x16x32_bf16 v[24:27], v[136:139], v[192:195], v[24:27]
	v_mfma_f32_16x16x32_bf16 v[12:15], v[128:131], v[200:203], v[12:15]
	v_mfma_f32_16x16x32_bf16 v[8:11], v[136:139], v[200:203], v[8:11]
	v_mfma_f32_16x16x32_bf16 v[60:63], v[132:135], v[180:183], v[60:63]
	v_mfma_f32_16x16x32_bf16 v[56:59], v[140:143], v[180:183], v[56:59]
	v_mfma_f32_16x16x32_bf16 v[44:47], v[132:135], v[188:191], v[44:47]
	v_mfma_f32_16x16x32_bf16 v[40:43], v[140:143], v[188:191], v[40:43]
	v_mfma_f32_16x16x32_bf16 v[28:31], v[132:135], v[196:199], v[28:31]
	v_mfma_f32_16x16x32_bf16 v[24:27], v[140:143], v[196:199], v[24:27]
	v_mfma_f32_16x16x32_bf16 v[12:15], v[132:135], v[204:207], v[12:15]
	v_mfma_f32_16x16x32_bf16 v[8:11], v[140:143], v[204:207], v[8:11]
	s_setprio 0
	s_setprio 1
	v_mfma_f32_16x16x32_bf16 v[52:55], v[156:159], v[176:179], v[52:55]
	v_mfma_f32_16x16x32_bf16 v[48:51], v[168:171], v[176:179], v[48:51]
	v_mfma_f32_16x16x32_bf16 v[36:39], v[156:159], v[184:187], v[36:39]
	v_mfma_f32_16x16x32_bf16 v[32:35], v[168:171], v[184:187], v[32:35]
	v_mfma_f32_16x16x32_bf16 v[20:23], v[156:159], v[192:195], v[20:23]
	v_mfma_f32_16x16x32_bf16 v[16:19], v[168:171], v[192:195], v[16:19]
	v_mfma_f32_16x16x32_bf16 v[4:7], v[156:159], v[200:203], v[4:7]
	v_mfma_f32_16x16x32_bf16 v[0:3], v[168:171], v[200:203], v[0:3]
	v_mfma_f32_16x16x32_bf16 v[52:55], v[164:167], v[180:183], v[52:55]
	v_mfma_f32_16x16x32_bf16 v[48:51], v[172:175], v[180:183], v[48:51]
	v_mfma_f32_16x16x32_bf16 v[36:39], v[164:167], v[188:191], v[36:39]
	v_mfma_f32_16x16x32_bf16 v[32:35], v[172:175], v[188:191], v[32:35]
	v_mfma_f32_16x16x32_bf16 v[20:23], v[164:167], v[196:199], v[20:23]
	v_mfma_f32_16x16x32_bf16 v[16:19], v[172:175], v[196:199], v[16:19]
	v_mfma_f32_16x16x32_bf16 v[4:7], v[164:167], v[204:207], v[4:7]
	v_mfma_f32_16x16x32_bf16 v[0:3], v[172:175], v[204:207], v[0:3]
	s_setprio 0
	s_barrier
; #define PG8_STAGE(bufoff, gbase, voff) do { _Pragma("unroll") for (int _i = 0; _i < 2; ++_i) \
;         __builtin_amdgcn_global_load_lds((const unsigned*)((const char*)(gbase) + (voff)[_i]), (PG8_LAS unsigned*)(lds + (bufoff) + ldsw + _i * 8192), 16, 0, 0); } while (0)
; #define PG8_LDA(dst, b, h) do { _Pragma("unroll") for (int m = 0; m < 4; ++m) _Pragma("unroll") for (int k = 0; k < 2; ++k) dst[m][k] = *(const PG8_LAS bf16x8*)(lds + PG8_SA(b, h) + aoff + m * 2048 + k * 1024); } while (0)
; #define PG8_LDB(dst, b, h) do { _Pragma("unroll") for (int n = 0; n < 2; ++n) _Pragma("unroll") for (int k = 0; k < 2; ++k) dst[n][k] = *(const PG8_LAS bf16x8*)(lds + PG8_SB(b, h) + boff + n * 2048 + k * 1024); } while (0)
; #define PG8_MMA(ai, bj, At, Bt) do { __builtin_amdgcn_s_setprio(1); _Pragma("unroll") for (int m = 0; m < 4; ++m) _Pragma("unroll") for (int n = 0; n < 2; ++n) _Pragma("unroll") for (int k = 0; k < 2; ++k) \
;         acc[ai][bj][m][n] = __builtin_amdgcn_mfma_f32_16x16x32_bf16(Bt[n][k], At[m][k], acc[ai][bj][m][n], 0, 0, 0); __builtin_amdgcn_s_setprio(0); } while (0)
; #define PG8_WAIT_V(n) asm volatile("s_waitcnt vmcnt(" #n ")" ::: "memory")
; #define PG8_WAIT_L(n) asm volatile("s_waitcnt lgkmcnt(" #n ")" ::: "memory")
; #define PG8_BAR __builtin_amdgcn_s_barrier()
; #define PG8_SCHED __builtin_amdgcn_sched_barrier(0)
; template <class Epi, class Sched, bool ALIGN_EPI = false, bool SP2 = false>
; __device__ __forceinline__ void gemm_phase(PG8_LAS unsigned char* lds, const Gemm g, const Sched& S, const Epi& E) {
;     ...
;             PG8_WAIT_V(8); PG8_WAIT_L(0); PG8_BAR; PG8_MMA(1, 0, At, B0); PG8_MMA(1, 1, At, B1); PG8_BAR; PG8_SCHED;
;             PG8_LDB(B0, 1, 0); PG8_LDB(B1, 1, 1); PG8_SCHED; PG8_LDA(At, 1, 0); PG8_STAGE(PG8_SA(0, 1), a2 + hstep, voffA);
;             PG8_WAIT_V(8); PG8_WAIT_L(0); PG8_BAR; PG8_MMA(0, 0, At, B0); PG8_MMA(0, 1, At, B1); PG8_BAR; PG8_SCHED;
;             PG8_LDA(At, 1, 1); PG8_STAGE(PG8_SB(1, 0), b3, voffB); PG8_STAGE(PG8_SB(1, 1), b3 + hstep, voffB); PG8_STAGE(PG8_SA(1, 0), a3, voffA);
;             PG8_WAIT_V(8); PG8_WAIT_L(0); PG8_BAR; PG8_MMA(1, 0, At, B0); PG8_MMA(1, 1, At, B1); PG8_BAR; PG8_SCHED;
	s_add_i32 s69, 0, 0x18000
	s_add_i32 s70, 0, 0x1c000
	v_add_u32_e32 v140, s69, v162
	v_add_u32_e32 v160, s70, v162
	ds_read_b128 v[128:131], v140
	ds_read_b128 v[132:135], v140 offset:1024
	ds_read_b128 v[136:139], v140 offset:2048
	ds_read_b128 v[140:143], v140 offset:3072
	ds_read_b128 v[156:159], v160
	ds_read_b128 v[164:167], v160 offset:1024
	ds_read_b128 v[168:171], v160 offset:2048
	ds_read_b128 v[172:175], v160 offset:3072
	s_add_u32 s64, s64, 0x4000
	s_addc_u32 s65, s65, 0
	s_mov_b32 m0, s41
	ds_read_b128 v[176:179], v163 offset:32768
	ds_read_b128 v[180:183], v163 offset:33792
	ds_read_b128 v[184:187], v163 offset:34816
	ds_read_b128 v[188:191], v163 offset:35840
	ds_read_b128 v[192:195], v163 offset:36864
	ds_read_b128 v[196:199], v163 offset:37888
	ds_read_b128 v[200:203], v163 offset:38912
	ds_read_b128 v[204:207], v163 offset:39936
	global_load_lds_dwordx4 v150, s[64:65]
	s_mov_b32 m0, s42
	s_nop 0
	global_load_lds_dwordx4 v146, s[64:65]
	s_waitcnt vmcnt(8)
	s_waitcnt lgkmcnt(0)
	s_barrier
	s_setprio 1
	s_waitcnt lgkmcnt(0)
	v_mfma_f32_16x16x32_bf16 v[124:127], v[128:131], v[176:179], v[124:127]
	v_mfma_f32_16x16x32_bf16 v[120:123], v[136:139], v[176:179], v[120:123]
	v_mfma_f32_16x16x32_bf16 v[108:111], v[128:131], v[184:187], v[108:111]
	v_mfma_f32_16x16x32_bf16 v[104:107], v[136:139], v[184:187], v[104:107]
	v_mfma_f32_16x16x32_bf16 v[92:95], v[128:131], v[192:195], v[92:95]
	v_mfma_f32_16x16x32_bf16 v[88:91], v[136:139], v[192:195], v[88:91]
	v_mfma_f32_16x16x32_bf16 v[76:79], v[128:131], v[200:203], v[76:79]
	v_mfma_f32_16x16x32_bf16 v[72:75], v[136:139], v[200:203], v[72:75]
	v_mfma_f32_16x16x32_bf16 v[124:127], v[132:135], v[180:183], v[124:127]
	v_mfma_f32_16x16x32_bf16 v[120:123], v[140:143], v[180:183], v[120:123]
	v_mfma_f32_16x16x32_bf16 v[108:111], v[132:135], v[188:191], v[108:111]
	v_mfma_f32_16x16x32_bf16 v[104:107], v[140:143], v[188:191], v[104:107]
	v_mfma_f32_16x16x32_bf16 v[92:95], v[132:135], v[196:199], v[92:95]
	v_mfma_f32_16x16x32_bf16 v[88:91], v[140:143], v[196:199], v[88:91]
	v_mfma_f32_16x16x32_bf16 v[76:79], v[132:135], v[204:207], v[76:79]
	v_mfma_f32_16x16x32_bf16 v[72:75], v[140:143], v[204:207], v[72:75]
	s_setprio 0
	s_setprio 1
	v_mfma_f32_16x16x32_bf16 v[116:119], v[156:159], v[176:179], v[116:119]
	v_mfma_f32_16x16x32_bf16 v[112:115], v[168:171], v[176:179], v[112:115]
	v_mfma_f32_16x16x32_bf16 v[100:103], v[156:159], v[184:187], v[100:103]
	v_mfma_f32_16x16x32_bf16 v[96:99], v[168:171], v[184:187], v[96:99]
	v_mfma_f32_16x16x32_bf16 v[84:87], v[156:159], v[192:195], v[84:87]
	v_mfma_f32_16x16x32_bf16 v[80:83], v[168:171], v[192:195], v[80:83]
	v_mfma_f32_16x16x32_bf16 v[68:71], v[156:159], v[200:203], v[68:71]
	v_mfma_f32_16x16x32_bf16 v[64:67], v[168:171], v[200:203], v[64:67]
	v_mfma_f32_16x16x32_bf16 v[116:119], v[164:167], v[180:183], v[116:119]
	v_mfma_f32_16x16x32_bf16 v[112:115], v[172:175], v[180:183], v[112:115]
	v_mfma_f32_16x16x32_bf16 v[100:103], v[164:167], v[188:191], v[100:103]
	v_mfma_f32_16x16x32_bf16 v[96:99], v[172:175], v[188:191], v[96:99]
	v_mfma_f32_16x16x32_bf16 v[84:87], v[164:167], v[196:199], v[84:87]
	v_mfma_f32_16x16x32_bf16 v[80:83], v[172:175], v[196:199], v[80:83]
	v_mfma_f32_16x16x32_bf16 v[68:71], v[164:167], v[204:207], v[68:71]
	v_mfma_f32_16x16x32_bf16 v[64:67], v[172:175], v[204:207], v[64:67]
	s_setprio 0
	s_barrier
	s_add_u32 s64, s62, 0x8000
	s_addc_u32 s65, s63, 0
	s_add_i32 s69, s69, s30
	s_mov_b32 m0, s69
	ds_read_b128 v[176:179], v163 offset:49152
	ds_read_b128 v[180:183], v163 offset:50176
	ds_read_b128 v[184:187], v163 offset:51200
	ds_read_b128 v[188:191], v163 offset:52224
	ds_read_b128 v[192:195], v163 offset:53248
	ds_read_b128 v[196:199], v163 offset:54272
	ds_read_b128 v[200:203], v163 offset:55296
	ds_read_b128 v[204:207], v163 offset:56320
	global_load_lds_dwordx4 v148, s[64:65]
	s_add_i32 m0, s69, 0x2000
	s_add_u32 s62, s62, 0xc000
	v_lshl_add_u64 v[160:161], s[64:65], 0, v[144:145]
	s_addc_u32 s63, s63, 0
	s_add_i32 s64, s70, s30
	global_load_lds_dwordx4 v[160:161], off
	s_mov_b32 m0, s64
	s_nop 0
	global_load_lds_dwordx4 v148, s[62:63]
	s_add_i32 m0, s64, 0x2000
	s_nop 0
	global_load_lds_dwordx4 v144, s[62:63]
	s_mov_b32 m0, s54
	s_nop 0
	global_load_lds_dwordx4 v150, s[20:21]
	s_mov_b32 m0, s55
	s_nop 0
	global_load_lds_dwordx4 v146, s[20:21]
	s_waitcnt vmcnt(8)
	s_waitcnt lgkmcnt(0)
	s_barrier
	s_setprio 1
	s_waitcnt lgkmcnt(0)
	v_mfma_f32_16x16x32_bf16 v[60:63], v[128:131], v[176:179], v[60:63]
	v_mfma_f32_16x16x32_bf16 v[56:59], v[136:139], v[176:179], v[56:59]
	v_mfma_f32_16x16x32_bf16 v[44:47], v[128:131], v[184:187], v[44:47]
	v_mfma_f32_16x16x32_bf16 v[40:43], v[136:139], v[184:187], v[40:43]
	v_mfma_f32_16x16x32_bf16 v[28:31], v[128:131], v[192:195], v[28:31]
	v_mfma_f32_16x16x32_bf16 v[24:27], v[136:139], v[192:195], v[24:27]
	v_mfma_f32_16x16x32_bf16 v[12:15], v[128:131], v[200:203], v[12:15]
	v_mfma_f32_16x16x32_bf16 v[8:11], v[136:139], v[200:203], v[8:11]
	v_mfma_f32_16x16x32_bf16 v[60:63], v[132:135], v[180:183], v[60:63]
	v_mfma_f32_16x16x32_bf16 v[56:59], v[140:143], v[180:183], v[56:59]
	v_mfma_f32_16x16x32_bf16 v[44:47], v[132:135], v[188:191], v[44:47]
	v_mfma_f32_16x16x32_bf16 v[40:43], v[140:143], v[188:191], v[40:43]
	v_mfma_f32_16x16x32_bf16 v[28:31], v[132:135], v[196:199], v[28:31]
	v_mfma_f32_16x16x32_bf16 v[24:27], v[140:143], v[196:199], v[24:27]
	v_mfma_f32_16x16x32_bf16 v[12:15], v[132:135], v[204:207], v[12:15]
	v_mfma_f32_16x16x32_bf16 v[8:11], v[140:143], v[204:207], v[8:11]
	s_setprio 0
	s_setprio 1
	v_mfma_f32_16x16x32_bf16 v[52:55], v[156:159], v[176:179], v[52:55]
	v_mfma_f32_16x16x32_bf16 v[48:51], v[168:171], v[176:179], v[48:51]
	v_mfma_f32_16x16x32_bf16 v[36:39], v[156:159], v[184:187], v[36:39]
	v_mfma_f32_16x16x32_bf16 v[32:35], v[168:171], v[184:187], v[32:35]
	v_mfma_f32_16x16x32_bf16 v[20:23], v[156:159], v[192:195], v[20:23]
	v_mfma_f32_16x16x32_bf16 v[16:19], v[168:171], v[192:195], v[16:19]
	v_mfma_f32_16x16x32_bf16 v[4:7], v[156:159], v[200:203], v[4:7]
	v_mfma_f32_16x16x32_bf16 v[0:3], v[168:171], v[200:203], v[0:3]
	v_mfma_f32_16x16x32_bf16 v[52:55], v[164:167], v[180:183], v[52:55]
	v_mfma_f32_16x16x32_bf16 v[48:51], v[172:175], v[180:183], v[48:51]
	v_mfma_f32_16x16x32_bf16 v[36:39], v[164:167], v[188:191], v[36:39]
	v_mfma_f32_16x16x32_bf16 v[32:35], v[172:175], v[188:191], v[32:35]
	v_mfma_f32_16x16x32_bf16 v[20:23], v[164:167], v[196:199], v[20:23]
	v_mfma_f32_16x16x32_bf16 v[16:19], v[172:175], v[196:199], v[16:19]
	v_mfma_f32_16x16x32_bf16 v[4:7], v[164:167], v[204:207], v[4:7]
	v_mfma_f32_16x16x32_bf16 v[0:3], v[172:175], v[204:207], v[0:3]
	s_setprio 0
	s_barrier
	s_add_i32 s68, s68, 2
	s_add_u32 s18, s18, 0x10000
	s_addc_u32 s19, s19, 0
	s_add_u32 s66, s66, 0x10000
	s_addc_u32 s67, s67, 0
	s_cmp_gt_u32 s68, 13
	s_cbranch_scc0 .LBB0_1356
	s_and_b64 vcc, exec, s[6:7]
	s_cbranch_vccz .LBB0_1359
	s_barrier
